# v15 + rcp wait-state slots filled with independent VALU (314 s_nops) + P11 attention unit: q-norm gain table loaded once per phase into v210-241, index loads issued with q-row loads, vmcnt recomputed
# speedup vs baseline: 1.0009x; 1.0009x over previous
; #define LAS __attribute__((address_space(3)))
; __global__ void __launch_bounds__(NTHR, 2) mk_fwd(Args args) {
;     ...
;             const int kvh = bid & 3, g = lane >> 4, lr = lane & 15, nslots = (G >> 2) * NWAVES;
;             const unsigned char* K8 = (const unsigned char*)(AP->ws + WS_K8);
;             if (tid == 0) ((volatile LAS int*)(lds + MISC_OFF))[12] = 0;
;             __syncthreads();
;             constexpr int NATT = 128, NLATE = 26;
;     ...
;                 for (int s = 0; s < 4; ++s) { const f32x4 g0 = *(const f32x4*)(b_q_norm + 32 * g + 8 * s), g1 = *(const f32x4*)(b_q_norm + 32 * g + 8 * s + 4);
.LBB0_5530:
	s_or_b64 exec, exec, s[4:5]
	s_mov_b32 s41, 0
	v_cmp_eq_u32_e32 vcc, 0, v79
	s_waitcnt lgkmcnt(0)
	s_barrier
	s_and_saveexec_b64 s[4:5], vcc
	s_add_i32 s3, 0, 0x228b0
	v_mov_b32_e32 v0, 0
	v_mov_b32_e32 v1, s3
	ds_write_b32 v1, v0
	s_or_b64 exec, exec, s[4:5]
	s_lshl_b32 s3, s28, 1
	s_and_b32 s8, s2, 3
	s_and_b32 s3, s3, -8
	s_add_u32 s44, s38, 0x4fc00000
	s_addc_u32 s45, s39, 0
	s_lshl_b32 s6, s2, 1
	s_and_b32 s29, s6, -8
	s_add_i32 s30, s97, 0
	s_add_u32 s31, s38, 0x4c000000
	s_addc_u32 s34, s39, 0
	v_lshlrev_b32_e32 v0, 8, v92
	s_add_u32 s46, s38, 0x3b400000
	v_ashrrev_i32_e32 v95, 4, v92
	v_and_b32_e32 v0, 0x300, v0
	s_addc_u32 s47, s39, 0
	s_lshl_b32 s9, s8, 4
	v_lshl_or_b32 v72, s8, 10, v0
	v_mov_b32_e32 v73, 0
	v_lshlrev_b32_e32 v74, 5, v95
	s_add_i32 s55, s9, 0
	v_lshl_add_u64 v[0:1], s[38:39], 0, v[72:73]
	v_ashrrev_i32_e32 v75, 31, v74
	s_lshl_b32 s35, s8, 20
	s_lshl_b32 s54, s8, 2
	s_add_i32 s55, s55, 0x20800
	s_lshl_b32 s56, s8, 8
	v_lshl_add_u64 v[0:1], v[74:75], 1, v[0:1]
	s_mov_b64 s[6:7], 0x35600000
	s_add_u32 s57, s38, 0x4c800000
	v_lshl_add_u64 v[76:77], v[0:1], 0, s[6:7]
	s_addc_u32 s58, s39, 0
	v_lshlrev_b32_e32 v0, 2, v92
	s_add_u32 s48, s38, 0xb600000
	v_and_b32_e32 v78, 60, v0
	v_lshlrev_b32_e32 v0, 3, v92
	s_addc_u32 s49, s39, 0
	v_and_b32_e32 v0, 56, v0
	s_add_u32 s50, s38, 0x8a00000
	v_mul_u32_u24_e32 v3, 0x104, v0
	v_lshlrev_b32_e32 v80, 1, v0
	v_mbcnt_lo_u32_b32 v0, -1, 0
	v_and_b32_e32 v2, 12, v92
	s_addc_u32 s51, s39, 0
	s_movk_i32 s8, 0x104
	v_ashrrev_i32_e32 v96, 3, v92
	v_mbcnt_hi_u32_b32 v93, -1, v0
	v_cmp_eq_u32_e64 s[6:7], 0, v2
	s_add_u32 s42, s38, 0x8200000
	v_lshl_add_u32 v1, v78, 2, s30
	v_mul_lo_u32 v2, v95, s8
	v_lshlrev_b32_e32 v4, 2, v96
	v_and_b32_e32 v101, 64, v93
	v_cmp_eq_u32_e64 s[4:5], 0, v92
	s_addc_u32 s43, s39, 0
	v_add3_u32 v97, s30, v3, v4
	s_add_i32 s59, 0, 0x228b0
	v_mov_b32_e32 v98, 0x358637bd
	s_mov_b32 s60, 0x800000
	s_movk_i32 s61, 0x80
	s_mov_b32 s62, 0xff61b1e6
	v_add_u32_e32 v99, v1, v2
	v_xor_b32_e32 v100, 16, v93
	v_add_u32_e32 v94, 64, v101
	v_xor_b32_e32 v102, 32, v93
	v_mov_b32_e32 v103, 0xff61b1e6
	s_load_dwordx2 s[98:99], s[22:23], 0x78
	s_waitcnt lgkmcnt(0)
	v_lshl_add_u64 v[242:243], v[74:75], 2, s[98:99]
	global_load_dwordx4 v[210:213], v[242:243], off
	global_load_dwordx4 v[214:217], v[242:243], off offset:16
	global_load_dwordx4 v[218:221], v[242:243], off offset:32
	global_load_dwordx4 v[222:225], v[242:243], off offset:48
	global_load_dwordx4 v[226:229], v[242:243], off offset:64
	global_load_dwordx4 v[230:233], v[242:243], off offset:80
	global_load_dwordx4 v[234:237], v[242:243], off offset:96
	global_load_dwordx4 v[238:241], v[242:243], off offset:112
	s_waitcnt vmcnt(0)
	s_waitcnt lgkmcnt(0)
	s_barrier
	s_branch .LBB0_5537

; #define LAS __attribute__((address_space(3)))
; DI float bf2f(unsigned b) { return __uint_as_float(b << 16); }
; DI void attn_unit_f8(LAS unsigned char* vbuf  , const LAS float* lut2  , const long (&qf)[4], const int* idx, int cnt_, int qpos_, int kvh, const unsigned char* K8, const bf16* VB, bf16* orow, int lane_) {
;     ...
;     for (int kt = 0; kt < 16; ++kt) R[kt] = idx[16 * kt + lr];
; __global__ void __launch_bounds__(NTHR, 2) mk_fwd(Args args) {
;     ...
;             for (;;) {
;             int it = 0;
;             if (lane == 0) it = __hip_atomic_fetch_add((LAS int*)(lds + MISC_OFF) + 12, 1, __ATOMIC_RELAXED, __HIP_MEMORY_SCOPE_WORKGROUP);
;             it = __builtin_amdgcn_readfirstlane(it);
;             if (it >= NATT + NLATE) break;
;             const int grp = it / 6, pos = it % 6;
;             const bool is_tr = (pos == 5 && grp < NLATE) ;
;             if (is_tr) { const int L = bid + G * (12 + grp); if (L < LATE_N) LATE_TR(L); continue; }
;             const int u = it - (grp < NLATE ? grp : NLATE);
;             if (u >= NATT) continue;
;             {
;                 const int t = (bid >> 2) * NWAVES + (u & 7) + nslots * (u >> 3);
;                 if (t >= T) continue;
;                 const bf16* qr = QRAW + (size_t)t * D + (4 * kvh + (lr & 3)) * 128;
;                 float qv[4][8]; float ss = 0.f;
; #pragma unroll
;                 for (int s = 0; s < 4; ++s) { const v4u w = *(const v4u*)(qr + 32 * g + 8 * s);
;                     qv[s][0] = bf2f(w.x & 0xffffu); qv[s][1] = bf2f(w.x >> 16); qv[s][2] = bf2f(w.y & 0xffffu); qv[s][3] = bf2f(w.y >> 16);
;                     qv[s][4] = bf2f(w.z & 0xffffu); qv[s][5] = bf2f(w.z >> 16); qv[s][6] = bf2f(w.w & 0xffffu); qv[s][7] = bf2f(w.w >> 16);
; #pragma unroll
;                     for (int e = 0; e < 8; ++e) ss += qv[s][e] * qv[s][e]; }
;                 ss += __shfl_xor(ss, 16); ss += __shfl_xor(ss, 32);
;                 const float rs = (lr < 4) ? rsqrtf(ss * (1.f / 128.f) + EPS) : 0.f;
.LBB0_5541:
	s_or_b64 exec, exec, s[8:9]
	v_readfirstlane_b32 s10, v0
	s_cmpk_gt_i32 s10, 0x99
	s_mov_b64 s[8:9], -1
	s_cbranch_scc1 .LBB0_5536
	s_mul_hi_i32 s40, s10, 0x2aaaaaab
	s_lshr_b32 s8, s40, 31
	s_add_i32 s40, s40, s8
	s_mul_i32 s8, s40, 6
	s_sub_i32 s8, s10, s8
	s_cmp_lg_u32 s8, 5
	s_mov_b64 s[8:9], -1
	s_cbranch_scc0 .LBB0_5551
	s_sub_i32 s8, s10, s40
	s_cmpk_gt_i32 s8, 0x7f
	s_cbranch_scc1 .LBB0_5550
	s_and_b32 s9, s8, 7
	s_ashr_i32 s8, s8, 3
	s_or_b32 s9, s9, s29
	s_mul_i32 s8, s8, s3
	s_add_i32 s52, s9, s8
	s_cmpk_gt_i32 s52, 0x1fff
	s_cbranch_scc1 .LBB0_5550
	s_ashr_i32 s53, s52, 31
	s_lshl_b64 s[8:9], s[52:53], 12
	v_lshl_add_u64 v[8:9], v[76:77], 0, s[8:9]
	global_load_dwordx4 v[0:3], v[8:9], off
	global_load_dwordx4 v[4:7], v[8:9], off offset:16
	global_load_dwordx4 v[34:37], v[8:9], off offset:32
	global_load_dwordx4 v[38:41], v[8:9], off offset:48
	s_lshl_b64 s[100:101], s[52:53], 10
	s_add_u32 s100, s31, s100
	s_addc_u32 s101, s34, s101
	v_and_b32_e32 v66, 15, v92
	v_lshlrev_b32_e32 v66, 2, v66
	global_load_dword v147, v66, s[100:101]
	global_load_dword v142, v66, s[100:101] offset:64
	global_load_dword v132, v66, s[100:101] offset:128
	global_load_dword v125, v66, s[100:101] offset:192
	global_load_dword v122, v66, s[100:101] offset:256
	global_load_dword v121, v66, s[100:101] offset:320
	global_load_dword v120, v66, s[100:101] offset:384
	global_load_dword v118, v66, s[100:101] offset:448
	global_load_dword v119, v66, s[100:101] offset:512
	global_load_dword v117, v66, s[100:101] offset:576
	global_load_dword v116, v66, s[100:101] offset:640
	global_load_dword v115, v66, s[100:101] offset:704
	global_load_dword v114, v66, s[100:101] offset:768
	global_load_dword v113, v66, s[100:101] offset:832
	global_load_dword v112, v66, s[100:101] offset:896
	global_load_dword v110, v66, s[100:101] offset:960
	v_cmp_lt_i32_e32 vcc, v100, v94
	s_waitcnt vmcnt(19)
	v_and_b32_e32 v30, 0xffff0000, v0
	v_cndmask_b32_e32 v8, v93, v100, vcc
	v_lshlrev_b32_e32 v72, 2, v8
	v_lshlrev_b32_e32 v29, 16, v0
	v_mul_f32_e32 v8, v30, v30
	v_lshlrev_b32_e32 v31, 16, v1
	v_fmac_f32_e32 v8, v29, v29
	v_and_b32_e32 v32, 0xffff0000, v1
	v_fmac_f32_e32 v8, v31, v31
	v_lshlrev_b32_e32 v25, 16, v2
	v_fmac_f32_e32 v8, v32, v32
	v_and_b32_e32 v26, 0xffff0000, v2
	v_fmac_f32_e32 v8, v25, v25
	v_lshlrev_b32_e32 v27, 16, v3
	v_fmac_f32_e32 v8, v26, v26
	v_and_b32_e32 v28, 0xffff0000, v3
	v_fmac_f32_e32 v8, v27, v27
	s_waitcnt vmcnt(18)
	v_lshlrev_b32_e32 v21, 16, v4
	v_fmac_f32_e32 v8, v28, v28
	v_and_b32_e32 v22, 0xffff0000, v4
	v_fmac_f32_e32 v8, v21, v21
	v_lshlrev_b32_e32 v23, 16, v5
	v_fmac_f32_e32 v8, v22, v22
	v_and_b32_e32 v24, 0xffff0000, v5
	v_fmac_f32_e32 v8, v23, v23
	v_lshlrev_b32_e32 v17, 16, v6
	v_fmac_f32_e32 v8, v24, v24
	v_and_b32_e32 v18, 0xffff0000, v6
	v_fmac_f32_e32 v8, v17, v17
	v_lshlrev_b32_e32 v19, 16, v7
	v_fmac_f32_e32 v8, v18, v18
	v_and_b32_e32 v20, 0xffff0000, v7
	v_fmac_f32_e32 v8, v19, v19
	s_waitcnt vmcnt(17)
	v_lshlrev_b32_e32 v13, 16, v34
	v_fmac_f32_e32 v8, v20, v20
	v_and_b32_e32 v14, 0xffff0000, v34
	v_fmac_f32_e32 v8, v13, v13
	v_lshlrev_b32_e32 v15, 16, v35
	v_fmac_f32_e32 v8, v14, v14
	v_and_b32_e32 v16, 0xffff0000, v35
	v_fmac_f32_e32 v8, v15, v15
	v_lshlrev_b32_e32 v9, 16, v36
	v_fmac_f32_e32 v8, v16, v16
	v_and_b32_e32 v10, 0xffff0000, v36
	v_fmac_f32_e32 v8, v9, v9
	v_lshlrev_b32_e32 v11, 16, v37
	v_fmac_f32_e32 v8, v10, v10
	v_and_b32_e32 v12, 0xffff0000, v37
	v_fmac_f32_e32 v8, v11, v11
	s_waitcnt vmcnt(16)
	v_lshlrev_b32_e32 v7, 16, v38
	v_fmac_f32_e32 v8, v12, v12
	v_and_b32_e32 v6, 0xffff0000, v38
	v_fmac_f32_e32 v8, v7, v7
	v_lshlrev_b32_e32 v5, 16, v39
	v_fmac_f32_e32 v8, v6, v6
	v_and_b32_e32 v4, 0xffff0000, v39
	v_fmac_f32_e32 v8, v5, v5
	v_lshlrev_b32_e32 v3, 16, v40
	v_fmac_f32_e32 v8, v4, v4
	v_and_b32_e32 v2, 0xffff0000, v40
	v_fmac_f32_e32 v8, v3, v3
	v_lshlrev_b32_e32 v1, 16, v41
	v_fmac_f32_e32 v8, v2, v2
	v_and_b32_e32 v0, 0xffff0000, v41
	v_fmac_f32_e32 v8, v1, v1
	v_fmac_f32_e32 v8, v0, v0
	s_waitcnt lgkmcnt(0)
	ds_bpermute_b32 v33, v72, v8
	v_cmp_lt_i32_e32 vcc, v102, v94
	s_waitcnt lgkmcnt(0)
	v_add_f32_e32 v33, v8, v33
	v_cndmask_b32_e32 v34, v93, v102, vcc
	v_lshlrev_b32_e32 v81, 2, v34
	ds_bpermute_b32 v34, v81, v33
	v_mov_b32_e32 v8, 0
	s_and_saveexec_b64 s[8:9], s[6:7]
	s_cbranch_execz .LBB0_5547
	s_waitcnt lgkmcnt(0)
	v_add_f32_e32 v8, v33, v34
	v_fmamk_f32 v8, v8, 0x3c000000, v98
	v_mul_f32_e32 v33, 0x4b800000, v8
	v_cmp_gt_f32_e32 vcc, s60, v8
	s_nop 1
	v_cndmask_b32_e32 v8, v8, v33, vcc
	v_rsq_f32_e32 v8, v8
	s_nop 0
	v_mul_f32_e32 v33, 0x45800000, v8
	v_cndmask_b32_e32 v8, v8, v33, vcc
; #define LAS __attribute__((address_space(3)))
; DI unsigned pk4_fp8(float a, float b, float c, float d) { int p = __builtin_amdgcn_cvt_pk_fp8_f32(a, b, 0, false); p = __builtin_amdgcn_cvt_pk_fp8_f32(c, d, p, true); return (unsigned)p; }
; DI void attn_unit_f8(LAS unsigned char* vbuf  , const LAS float* lut2  , const long (&qf)[4], const int* idx, int cnt_, int qpos_, int kvh, const unsigned char* K8, const bf16* VB, bf16* orow, int lane_) {
;     ...
; #pragma unroll
;     for (int i = 0; i < 8; ++i) A8_ISSUE_K(i);
;     f32x4 lg[16]; f32x4 o[8]; bf16x8 pf[8]; float inv = 0.f;
;     const int hcol = 4 * kvh + (lr & 3);
; #pragma unroll
;     for (int i = 0; i < 16; ++i) {
;         asm volatile("" ::: "memory");
;         {
;             int kp4[4];
; #pragma unroll
;             for (int e = 0; e < 4; ++e) kp4[e] = __shfl(R[i], 4 * g + e);
;             f32x4 acc = (f32x4){0.f, 0.f, 0.f, 0.f};
; #pragma unroll
;             for (int s = 0; s < 4; ++s) { const v4u w = ring[(2 * i + (s >> 1)) & 15]; const unsigned long long ka = (s & 1) ? ((unsigned long long)w.w << 32 | w.z) : ((unsigned long long)w.y << 32 | w.x);
;                 acc = __builtin_amdgcn_mfma_f32_16x16x32_fp8_fp8((long)ka, qf[s], acc, 0, 0, 0); }
;             float bs[4]; bool okv[4];
; #pragma unroll
;             for (int e = 0; e < 4; ++e) { const int rel = qpos - kp4[e]; okv[e] = (4 * g + e < cnt - 16 * i) && rel >= 0; const int rc = rel > 128 ? 128 : (rel < 0 ? 0 : rel); bs[e] = lut2[rc * 16 + hcol]; }
; __global__ void __launch_bounds__(NTHR, 2) mk_fwd(Args args) {
;     ...
;                 long qf[4];
; #pragma unroll
;                 for (int s = 0; s < 4; ++s) { const f32x4 g0 = *(const f32x4*)(b_q_norm + 32 * g + 8 * s), g1 = *(const f32x4*)(b_q_norm + 32 * g + 8 * s + 4);
;                     const unsigned lo = pk4_fp8(qv[s][0] * rs * g0[0], qv[s][1] * rs * g0[1], qv[s][2] * rs * g0[2], qv[s][3] * rs * g0[3]);
;                     const unsigned hi = pk4_fp8(qv[s][4] * rs * g1[0], qv[s][5] * rs * g1[1], qv[s][6] * rs * g1[2], qv[s][7] * rs * g1[3]);
;                     qf[s] = (long)(((unsigned long long)hi << 32) | lo); }
;                 const int cnt = t + 1 < TOPK ? t + 1 : TOPK;
;                 attn_unit_f8(lds + wave * WSLAB, (const LAS float*)(lds + LUT_OFF), qf, IDX + (size_t)t * TOPK, cnt, t, kvh, K8, VB, OATT + (size_t)t * D, lane);
.LBB0_5547:
	s_or_b64 exec, exec, s[8:9]
	v_mul_f32_e32 v62, v8, v30
	v_mul_f32_e32 v63, v8, v31
	v_mul_f32_e32 v64, v8, v32
	s_min_i32 s63, s52, 0xff
	s_waitcnt lgkmcnt(0)
	s_nop 0
	s_lshl_b64 s[8:9], s[52:53], 10
	v_mov_b32_e32 v65, v92
	s_add_u32 s8, s31, s8
	s_addc_u32 s9, s34, s9
	v_and_b32_e32 v83, 15, v65
	v_lshlrev_b32_e32 v66, 2, v83
	v_mul_f32_e32 v17, v8, v17
	v_mul_f32_e32 v18, v8, v18
	v_mul_f32_e32 v13, v8, v13
	v_mul_f32_e32 v14, v8, v14
	v_mul_f32_e32 v7, v8, v7
	v_mul_f32_e32 v6, v8, v6
	v_mov_b32_e32 v87, v73
	v_mov_b32_e32 v88, v73
	v_mov_b32_e32 v90, v73
	v_mul_f32_e32 v5, v8, v5
	v_mul_f32_e32 v3, v8, v3
	v_mul_f32_e32 v2, v8, v2
	v_ashrrev_i32_e32 v148, 4, v65
	v_mul_f32_e32 v19, v8, v19
	v_mul_f32_e32 v20, v8, v20
	v_mul_f32_e32 v15, v8, v15
	v_mul_f32_e32 v16, v8, v16
	v_mul_f32_e32 v4, v8, v4
	v_mov_b32_e32 v91, v73
	v_mul_f32_e32 v1, v8, v1
	v_mul_f32_e32 v0, v8, v0
	v_mul_f32_e32 v25, v8, v25
	v_mul_f32_e32 v26, v8, v26
	v_mul_f32_e32 v21, v8, v21
	v_mul_f32_e32 v22, v8, v22
	v_mul_f32_e32 v9, v8, v9
	v_mul_f32_e32 v10, v8, v10
	v_mul_f32_e32 v29, v8, v29
	v_mul_f32_e32 v27, v8, v27
	v_mul_f32_e32 v28, v8, v28
	v_mov_b32_e32 v85, v73
	v_mul_f32_e32 v23, v8, v23
	v_mul_f32_e32 v24, v8, v24
	v_mov_b32_e32 v86, v73
	v_mul_f32_e32 v11, v8, v11
	v_mul_f32_e32 v12, v8, v12
	v_mov_b32_e32 v89, v73
	v_bfe_u32 v8, v65, 1, 1
	v_lshlrev_b32_e32 v82, 2, v148
	v_mov_b32_e32 v84, v73
	v_cmp_ge_i32_e32 vcc, s63, v82
	v_cmp_gt_i32_e64 s[10:11], s63, v82
	v_or_b32_e32 v141, 2, v82
	v_cmp_ge_i32_e64 s[14:15], s63, v141
	v_or_b32_e32 v139, 3, v82
	v_cmp_ge_i32_e64 s[18:19], s63, v139
	v_or_b32_e32 v140, 1, v82
	v_lshl_or_b32 v111, v83, 4, s56
	s_waitcnt vmcnt(16)
	v_mul_f32_e32 v29, v210, v29
	s_waitcnt vmcnt(16)
	v_mul_f32_e32 v25, v214, v25
	v_mul_f32_e32 v26, v215, v26
	s_waitcnt vmcnt(16)
	v_mul_f32_e32 v17, v222, v17
	v_mul_f32_e32 v18, v223, v18
	s_waitcnt vmcnt(16)
	v_mul_f32_e32 v13, v226, v13
	v_mul_f32_e32 v14, v227, v14
	s_waitcnt vmcnt(16)
	v_mul_f32_e32 v7, v234, v7
	v_mul_f32_e32 v6, v235, v6
	v_cvt_pk_fp8_f32 v87, v17, v18
	v_cvt_pk_fp8_f32 v88, v13, v14
	v_cvt_pk_fp8_f32 v90, v7, v6
	v_mul_f32_e32 v5, v236, v5
	v_mul_f32_e32 v3, v238, v3
	v_mul_f32_e32 v2, v239, v2
	v_lshl_add_u32 v60, v148, 5, s35
	v_mul_f32_e32 v19, v224, v19
	v_mul_f32_e32 v20, v225, v20
	v_mul_f32_e32 v15, v228, v15
	v_mul_f32_e32 v16, v229, v16
	v_mul_f32_e32 v4, v237, v4
	v_cvt_pk_fp8_f32 v91, v3, v2
	s_waitcnt vmcnt(15)
	v_lshl_add_u32 v2, v147, 7, v60
	v_cvt_pk_fp8_f32 v87, v19, v20 op_sel:[0,0,1]
	v_cvt_pk_fp8_f32 v88, v15, v16 op_sel:[0,0,1]
	v_cvt_pk_fp8_f32 v90, v5, v4 op_sel:[0,0,1]
	global_load_dwordx4 v[4:7], v2, s[44:45] offset:16
	global_load_dwordx4 v[16:19], v2, s[44:45]
	v_mul_f32_e32 v1, v240, v1
	v_mul_f32_e32 v0, v241, v0
	v_cvt_pk_fp8_f32 v91, v1, v0 op_sel:[0,0,1]
	v_lshl_add_u32 v1, v148, 11, s30
	v_lshlrev_b32_e32 v2, 3, v65
	v_and_or_b32 v1, v2, 8, v1
	v_lshlrev_b32_e32 v2, 1, v148
	v_mul_f32_e32 v21, v218, v21
	v_mul_f32_e32 v22, v219, v22
	v_mul_f32_e32 v9, v230, v9
	v_mul_f32_e32 v10, v231, v10
	v_bfe_u32 v0, v65, 2, 2
	v_and_b32_e32 v3, 2, v2
	v_cvt_pk_fp8_f32 v85, v25, v26
	v_cvt_pk_fp8_f32 v86, v21, v22
	v_cvt_pk_fp8_f32 v89, v9, v10
	v_lshl_add_u32 v1, v0, 6, v1
	v_or_b32_e32 v9, v3, v8
	v_lshl_add_u32 v104, v9, 4, v1
	v_or_b32_e32 v9, 2, v8
	v_mul_f32_e32 v34, v211, v62
	v_bitop3_b32 v126, v3, v8, 1 bitop3:0x36
	v_bitop3_b32 v62, v3, v9, 1 bitop3:0x36
	v_lshlrev_b32_e32 v3, 6, v148
	v_mul_f32_e32 v27, v216, v27
	v_mul_f32_e32 v28, v217, v28
	v_mul_f32_e32 v23, v220, v23
	v_mul_f32_e32 v24, v221, v24
	v_mul_f32_e32 v11, v232, v11
	v_mul_f32_e32 v12, v233, v12
	v_lshl_add_u32 v123, v0, 9, v3
	s_waitcnt vmcnt(16)
	v_lshl_add_u32 v0, v142, 7, v60
	v_cvt_pk_fp8_f32 v85, v27, v28 op_sel:[0,0,1]
	v_cvt_pk_fp8_f32 v86, v23, v24 op_sel:[0,0,1]
	v_cvt_pk_fp8_f32 v89, v11, v12 op_sel:[0,0,1]
	v_bitop3_b32 v2, v8, v2, 2 bitop3:0x72
	global_load_dwordx4 v[8:11], v0, s[44:45] offset:16
	global_load_dwordx4 v[24:27], v0, s[44:45]
	s_waitcnt vmcnt(17)
	v_lshl_add_u32 v0, v132, 7, v60
	global_load_dwordx4 v[56:59], v0, s[44:45] offset:16
	global_load_dwordx4 v[150:153], v0, s[44:45]
	v_and_b32_e32 v61, 3, v65
	v_lshlrev_b32_e32 v124, 4, v61
	v_lshl_add_u32 v133, v61, 2, s55
	v_and_or_b32 v61, v82, 60, v101
	v_add_u32_e32 v127, 0x100, v1
	v_lshlrev_b32_e32 v138, 2, v61
	v_cvt_pk_fp8_f32 v84, v29, v34
	v_lshl_add_u32 v106, v62, 4, v127
	ds_bpermute_b32 v62, v138, v147 offset:4
	v_mul_f32_e32 v35, v212, v63
	ds_bpermute_b32 v63, v138, v147 offset:8
	v_mul_f32_e32 v36, v213, v64
	v_cvt_pk_fp8_f32 v84, v35, v36 op_sel:[0,0,1]
	s_waitcnt lgkmcnt(1)
	v_sub_u32_e32 v62, s52, v62
	v_cmp_lt_i32_e64 s[12:13], -1, v62
	v_med3_i32 v62, v62, 0, s61
	v_lshl_add_u32 v67, v62, 6, v133
	s_waitcnt lgkmcnt(0)
	v_sub_u32_e32 v62, s52, v63
	s_waitcnt vmcnt(18)
	v_lshl_add_u32 v0, v125, 7, v60
	v_cmp_lt_i32_e64 s[16:17], -1, v62
	v_med3_i32 v68, v62, 0, s61
	global_load_dwordx4 v[20:23], v0, s[44:45] offset:16
	global_load_dwordx4 v[28:31], v0, s[44:45]
	ds_bpermute_b32 v61, v138, v147
	s_waitcnt vmcnt(6)
	v_mfma_f32_16x16x32_fp8_fp8 v[62:65], v[16:17], v[84:85], 0
	ds_bpermute_b32 v66, v138, v147 offset:12
	v_lshl_add_u32 v0, v122, 7, v60
	global_load_dwordx4 v[32:35], v0, s[44:45] offset:16
	global_load_dwordx4 v[40:43], v0, s[44:45]
	v_mfma_f32_16x16x32_fp8_fp8 v[16:19], v[18:19], v[86:87], v[62:65]
	v_lshl_add_u32 v0, v121, 7, v60
	s_waitcnt lgkmcnt(1)
	v_sub_u32_e32 v61, s52, v61
	s_waitcnt lgkmcnt(0)
; #define A8_ISSUE_K(kt) do { const char* kr_ = (const char*)K8 + (unsigned)(R[kt] * 512 + kvh * 128 + 32 * g); ring[(2 * (kt)) & 15] = *(const v4u*)kr_; ring[(2 * (kt) + 1) & 15] = *(const v4u*)(kr_ + 16); } while (0)
; #define A8_ISSUE_V(hc) do { _Pragma("unroll") for (int q2_ = 0; q2_ < 4; ++q2_) { const int rid_ = __shfl(R[hc], 4 * q2_ + g); \
;         ring[(4 * (hc) + q2_) & 15] = *(const v4u*)((const char*)VB + (unsigned)(rid_ * 1024 + kvh * 256 + 16 * lr)); } } while (0)
; DI void attn_unit_f8(LAS unsigned char* vbuf  , const LAS float* lut2  , const long (&qf)[4], const int* idx, int cnt_, int qpos_, int kvh, const unsigned char* K8, const bf16* VB, bf16* orow, int lane_) {
;     ...
;     for (int i = 0; i < 16; ++i) {
;         asm volatile("" ::: "memory");
;         {
;             int kp4[4];
; #pragma unroll
;             for (int e = 0; e < 4; ++e) kp4[e] = __shfl(R[i], 4 * g + e);
;             f32x4 acc = (f32x4){0.f, 0.f, 0.f, 0.f};
; #pragma unroll
;             for (int s = 0; s < 4; ++s) { const v4u w = ring[(2 * i + (s >> 1)) & 15]; const unsigned long long ka = (s & 1) ? ((unsigned long long)w.w << 32 | w.z) : ((unsigned long long)w.y << 32 | w.x);
;                 acc = __builtin_amdgcn_mfma_f32_16x16x32_fp8_fp8((long)ka, qf[s], acc, 0, 0, 0); }
;             float bs[4]; bool okv[4];
; #pragma unroll
;             for (int e = 0; e < 4; ++e) { const int rel = qpos - kp4[e]; okv[e] = (4 * g + e < cnt - 16 * i) && rel >= 0; const int rc = rel > 128 ? 128 : (rel < 0 ? 0 : rel); bs[e] = lut2[rc * 16 + hcol]; }
;             asm volatile("" : "+v"(bs[0]), "+v"(bs[1]), "+v"(bs[2]), "+v"(bs[3]));
; #pragma unroll
;             for (int e = 0; e < 4; ++e) acc[e] = okv[e] ? acc[e] * (0.08838834764831845f * 1.4426950408889634f) + bs[e] : -3.0e38f;
;             lg[i] = acc;
;         }
;         if (i + 8 < 16) A8_ISSUE_K(i + 8);
;         else if ((i & 1) == 1) A8_ISSUE_V((i - 9) / 2);
	v_sub_u32_e32 v66, s52, v66
	global_load_dwordx4 v[36:39], v0, s[44:45] offset:16
	global_load_dwordx4 v[44:47], v0, s[44:45]
	v_lshl_add_u32 v0, v120, 7, v60
	v_lshl_add_u32 v12, v118, 7, v60
	v_cmp_lt_i32_e64 s[8:9], -1, v61
	v_med3_i32 v61, v61, 0, s61
	v_med3_i32 v62, v66, 0, s61
	v_mfma_f32_16x16x32_fp8_fp8 v[16:19], v[4:5], v[88:89], v[16:19]
	v_lshl_add_u32 v105, v2, 4, v1
	global_load_dwordx4 v[48:51], v0, s[44:45] offset:16
	global_load_dwordx4 v[52:55], v0, s[44:45]
	s_nop 0
	global_load_dwordx4 v[0:3], v12, s[44:45] offset:16
	s_nop 0
	global_load_dwordx4 v[12:15], v12, s[44:45]
	v_lshl_add_u32 v61, v61, 6, v133
	v_lshl_add_u32 v62, v62, 6, v133
	v_lshl_add_u32 v68, v68, 6, v133
	ds_read_b32 v62, v62
	ds_read_b32 v63, v68
	ds_read_b32 v64, v67
	ds_read_b32 v61, v61
	v_mfma_f32_16x16x32_fp8_fp8 v[4:7], v[6:7], v[90:91], v[16:19]
	s_waitcnt lgkmcnt(0)
	s_and_b64 vcc, vcc, s[8:9]
	s_nop 5
	v_fmac_f32_e32 v61, 0x3e0293ee, v4
	v_cndmask_b32_e32 v128, v103, v61, vcc
	v_fmac_f32_e32 v64, 0x3e0293ee, v5
	s_and_b64 vcc, s[10:11], s[12:13]
	s_waitcnt vmcnt(14)
	v_lshl_add_u32 v16, v119, 7, v60
	v_cmp_lt_i32_e64 s[20:21], -1, v66
	v_cndmask_b32_e32 v129, v103, v64, vcc
	v_fmac_f32_e32 v63, 0x3e0293ee, v6
	v_fmac_f32_e32 v62, 0x3e0293ee, v7
	global_load_dwordx4 v[4:7], v16, s[44:45] offset:16
	global_load_dwordx4 v[64:67], v16, s[44:45]
	ds_bpermute_b32 v16, v138, v142
	ds_bpermute_b32 v17, v138, v142 offset:4
	ds_bpermute_b32 v18, v138, v142 offset:8
	s_and_b64 vcc, s[14:15], s[16:17]
	v_cndmask_b32_e32 v130, v103, v63, vcc
	s_waitcnt lgkmcnt(2)
	v_sub_u32_e32 v16, s52, v16
	s_and_b64 vcc, s[18:19], s[20:21]
	v_cmp_lt_i32_e64 s[8:9], -1, v16
	v_med3_i32 v16, v16, 0, s61
	v_cndmask_b32_e32 v131, v103, v62, vcc
	v_lshl_add_u32 v62, v16, 6, v133
	s_waitcnt lgkmcnt(1)
	v_sub_u32_e32 v16, s52, v17
	v_cmp_lt_i32_e64 s[12:13], -1, v16
	v_med3_i32 v16, v16, 0, s61
	v_lshl_add_u32 v63, v16, 6, v133
	s_waitcnt lgkmcnt(0)
	v_sub_u32_e32 v68, s52, v18
	s_waitcnt vmcnt(14)
	v_mfma_f32_16x16x32_fp8_fp8 v[16:19], v[24:25], v[84:85], 0
	ds_bpermute_b32 v61, v138, v142 offset:12
	v_med3_i32 v24, v68, 0, s61
	v_mfma_f32_16x16x32_fp8_fp8 v[16:19], v[26:27], v[86:87], v[16:19]
	v_lshl_add_u32 v24, v24, 6, v133
	s_waitcnt lgkmcnt(0)
	v_sub_u32_e32 v25, s52, v61
	v_med3_i32 v26, v25, 0, s61
	v_mfma_f32_16x16x32_fp8_fp8 v[16:19], v[8:9], v[88:89], v[16:19]
	v_lshl_add_u32 v26, v26, 6, v133
	ds_read_b32 v26, v26
	ds_read_b32 v24, v24
	ds_read_b32 v27, v63
	ds_read_b32 v61, v62
	s_waitcnt lgkmcnt(0)
	v_mfma_f32_16x16x32_fp8_fp8 v[8:11], v[10:11], v[90:91], v[16:19]
	v_cmp_lt_i32_e64 s[16:17], -1, v68
	s_add_i32 s18, s63, -15
	v_cmp_gt_i32_e32 vcc, s18, v82
	v_lshl_add_u32 v16, v117, 7, v60
	ds_bpermute_b32 v17, v138, v132 offset:4
	s_nop 2
	v_fmac_f32_e32 v61, 0x3e0293ee, v8
	v_fmac_f32_e32 v27, 0x3e0293ee, v9
	v_fmac_f32_e32 v24, 0x3e0293ee, v10
	v_fmac_f32_e32 v26, 0x3e0293ee, v11
	global_load_dwordx4 v[8:11], v16, s[44:45] offset:16
	global_load_dwordx4 v[68:71], v16, s[44:45]
	ds_bpermute_b32 v16, v138, v132
	ds_bpermute_b32 v18, v138, v132 offset:8
	v_cmp_gt_i32_e64 s[10:11], s18, v140
	s_and_b64 vcc, vcc, s[8:9]
	v_cmp_gt_i32_e64 s[14:15], s18, v141
	s_waitcnt lgkmcnt(1)
	v_sub_u32_e32 v16, s52, v16
	v_cndmask_b32_e32 v134, v103, v61, vcc
	s_and_b64 vcc, s[10:11], s[12:13]
	v_cmp_lt_i32_e64 s[8:9], -1, v16
	v_med3_i32 v16, v16, 0, s61
	v_cmp_gt_i32_e64 s[18:19], s18, v139
	v_cmp_lt_i32_e64 s[20:21], -1, v25
	v_cndmask_b32_e32 v135, v103, v27, vcc
	s_and_b64 vcc, s[14:15], s[16:17]
	v_lshl_add_u32 v25, v16, 6, v133
	v_sub_u32_e32 v16, s52, v17
	v_cndmask_b32_e32 v136, v103, v24, vcc
	s_and_b64 vcc, s[18:19], s[20:21]
	v_cmp_lt_i32_e64 s[12:13], -1, v16
	v_med3_i32 v16, v16, 0, s61
	v_cndmask_b32_e32 v137, v103, v26, vcc
	v_lshl_add_u32 v26, v16, 6, v133
	s_waitcnt lgkmcnt(0)
	v_sub_u32_e32 v27, s52, v18
	s_waitcnt vmcnt(14)
	v_mfma_f32_16x16x32_fp8_fp8 v[16:19], v[150:151], v[84:85], 0
	ds_bpermute_b32 v24, v138, v132 offset:12
	v_cmp_lt_i32_e64 s[16:17], -1, v27
	v_med3_i32 v27, v27, 0, s61
	v_mfma_f32_16x16x32_fp8_fp8 v[16:19], v[152:153], v[86:87], v[16:19]
	s_waitcnt lgkmcnt(0)
	v_sub_u32_e32 v24, s52, v24
	v_med3_i32 v61, v24, 0, s61
	v_mfma_f32_16x16x32_fp8_fp8 v[16:19], v[56:57], v[88:89], v[16:19]
	v_lshl_add_u32 v27, v27, 6, v133
	v_lshl_add_u32 v61, v61, 6, v133
	ds_read_b32 v56, v61
	ds_read_b32 v27, v27
	ds_read_b32 v26, v26
	ds_read_b32 v25, v25
	v_mfma_f32_16x16x32_fp8_fp8 v[16:19], v[58:59], v[90:91], v[16:19]
	s_sub_i32 s18, s63, 31
	v_cmp_gt_i32_e32 vcc, s18, v82
	s_waitcnt lgkmcnt(0)
	v_cmp_gt_i32_e64 s[10:11], s18, v140
	s_nop 3
	v_fmac_f32_e32 v25, 0x3e0293ee, v16
	s_and_b64 vcc, vcc, s[8:9]
	v_cmp_gt_i32_e64 s[14:15], s18, v141
	v_cndmask_b32_e32 v143, v103, v25, vcc
	v_fmac_f32_e32 v26, 0x3e0293ee, v17
	s_and_b64 vcc, s[10:11], s[12:13]
	v_cmp_gt_i32_e64 s[18:19], s18, v139
	v_cmp_lt_i32_e64 s[20:21], -1, v24
	v_cndmask_b32_e32 v144, v103, v26, vcc
	v_fmac_f32_e32 v27, 0x3e0293ee, v18
	s_and_b64 vcc, s[14:15], s[16:17]
	v_cndmask_b32_e32 v145, v103, v27, vcc
	v_fmac_f32_e32 v56, 0x3e0293ee, v19
	s_and_b64 vcc, s[18:19], s[20:21]
	v_cndmask_b32_e32 v146, v103, v56, vcc
	ds_bpermute_b32 v56, v138, v125
	ds_bpermute_b32 v57, v138, v125 offset:4
	ds_bpermute_b32 v58, v138, v125 offset:8
	ds_bpermute_b32 v61, v138, v125 offset:12
	v_lshl_add_u32 v24, v116, 7, v60
	s_waitcnt lgkmcnt(3)
	v_sub_u32_e32 v56, s52, v56
	v_cmp_lt_i32_e64 s[8:9], -1, v56
	v_med3_i32 v56, v56, 0, s61
	v_lshl_add_u32 v62, v56, 6, v133
	s_waitcnt lgkmcnt(2)
	v_sub_u32_e32 v56, s52, v57
	v_cmp_lt_i32_e64 s[12:13], -1, v56
	v_med3_i32 v56, v56, 0, s61
	v_lshl_add_u32 v63, v56, 6, v133
	s_waitcnt lgkmcnt(1)
; #define A8_ISSUE_K(kt) do { const char* kr_ = (const char*)K8 + (unsigned)(R[kt] * 512 + kvh * 128 + 32 * g); ring[(2 * (kt)) & 15] = *(const v4u*)kr_; ring[(2 * (kt) + 1) & 15] = *(const v4u*)(kr_ + 16); } while (0)
; #define A8_ISSUE_V(hc) do { _Pragma("unroll") for (int q2_ = 0; q2_ < 4; ++q2_) { const int rid_ = __shfl(R[hc], 4 * q2_ + g); \
;         ring[(4 * (hc) + q2_) & 15] = *(const v4u*)((const char*)VB + (unsigned)(rid_ * 1024 + kvh * 256 + 16 * lr)); } } while (0)
; DI void attn_unit_f8(LAS unsigned char* vbuf  , const LAS float* lut2  , const long (&qf)[4], const int* idx, int cnt_, int qpos_, int kvh, const unsigned char* K8, const bf16* VB, bf16* orow, int lane_) {
;     ...
;     for (int i = 0; i < 16; ++i) {
;         asm volatile("" ::: "memory");
;         {
;             int kp4[4];
; #pragma unroll
;             for (int e = 0; e < 4; ++e) kp4[e] = __shfl(R[i], 4 * g + e);
;             f32x4 acc = (f32x4){0.f, 0.f, 0.f, 0.f};
; #pragma unroll
;             for (int s = 0; s < 4; ++s) { const v4u w = ring[(2 * i + (s >> 1)) & 15]; const unsigned long long ka = (s & 1) ? ((unsigned long long)w.w << 32 | w.z) : ((unsigned long long)w.y << 32 | w.x);
;                 acc = __builtin_amdgcn_mfma_f32_16x16x32_fp8_fp8((long)ka, qf[s], acc, 0, 0, 0); }
;             float bs[4]; bool okv[4];
; #pragma unroll
;             for (int e = 0; e < 4; ++e) { const int rel = qpos - kp4[e]; okv[e] = (4 * g + e < cnt - 16 * i) && rel >= 0; const int rc = rel > 128 ? 128 : (rel < 0 ? 0 : rel); bs[e] = lut2[rc * 16 + hcol]; }
;             asm volatile("" : "+v"(bs[0]), "+v"(bs[1]), "+v"(bs[2]), "+v"(bs[3]));
; #pragma unroll
;             for (int e = 0; e < 4; ++e) acc[e] = okv[e] ? acc[e] * (0.08838834764831845f * 1.4426950408889634f) + bs[e] : -3.0e38f;
;             lg[i] = acc;
;         }
;         if (i + 8 < 16) A8_ISSUE_K(i + 8);
;         else if ((i & 1) == 1) A8_ISSUE_V((i - 9) / 2);
	v_sub_u32_e32 v149, s52, v58
	s_waitcnt vmcnt(12)
	v_mfma_f32_16x16x32_fp8_fp8 v[56:59], v[28:29], v[84:85], 0
	v_med3_i32 v28, v149, 0, s61
	v_cmp_lt_i32_e64 s[16:17], -1, v149
	v_lshl_add_u32 v149, v28, 6, v133
	v_mfma_f32_16x16x32_fp8_fp8 v[28:31], v[30:31], v[86:87], v[56:59]
	s_waitcnt lgkmcnt(0)
	v_sub_u32_e32 v61, s52, v61
	global_load_dwordx4 v[16:19], v24, s[44:45] offset:16
	s_nop 0
	global_load_dwordx4 v[24:27], v24, s[44:45]
	v_med3_i32 v56, v61, 0, s61
	v_mfma_f32_16x16x32_fp8_fp8 v[28:31], v[20:21], v[88:89], v[28:31]
	v_lshl_add_u32 v56, v56, 6, v133
	ds_read_b32 v56, v56
	ds_read_b32 v57, v149
	ds_read_b32 v58, v63
	ds_read_b32 v59, v62
	v_mfma_f32_16x16x32_fp8_fp8 v[20:23], v[22:23], v[90:91], v[28:31]
	s_sub_i32 s18, s63, 47
	v_cmp_gt_i32_e32 vcc, s18, v82
	s_waitcnt lgkmcnt(0)
	v_cmp_gt_i32_e64 s[10:11], s18, v140
	s_nop 3
	v_fmac_f32_e32 v59, 0x3e0293ee, v20
	s_and_b64 vcc, vcc, s[8:9]
	v_cmp_gt_i32_e64 s[14:15], s18, v141
	v_cndmask_b32_e32 v150, v103, v59, vcc
	v_fmac_f32_e32 v58, 0x3e0293ee, v21
	s_and_b64 vcc, s[10:11], s[12:13]
	v_cmp_gt_i32_e64 s[18:19], s18, v139
	v_cmp_lt_i32_e64 s[20:21], -1, v61
	v_cndmask_b32_e32 v151, v103, v58, vcc
	v_fmac_f32_e32 v57, 0x3e0293ee, v22
	s_and_b64 vcc, s[14:15], s[16:17]
	v_cndmask_b32_e32 v152, v103, v57, vcc
	v_fmac_f32_e32 v56, 0x3e0293ee, v23
	s_and_b64 vcc, s[18:19], s[20:21]
	v_cndmask_b32_e32 v153, v103, v56, vcc
	ds_bpermute_b32 v56, v138, v122
	ds_bpermute_b32 v57, v138, v122 offset:4
	ds_bpermute_b32 v58, v138, v122 offset:8
	ds_bpermute_b32 v61, v138, v122 offset:12
	v_lshl_add_u32 v28, v115, 7, v60
	s_waitcnt lgkmcnt(3)
	v_sub_u32_e32 v56, s52, v56
	v_cmp_lt_i32_e64 s[8:9], -1, v56
	v_med3_i32 v56, v56, 0, s61
	v_lshl_add_u32 v62, v56, 6, v133
	s_waitcnt lgkmcnt(2)
	v_sub_u32_e32 v56, s52, v57
	v_cmp_lt_i32_e64 s[12:13], -1, v56
	v_med3_i32 v56, v56, 0, s61
	v_lshl_add_u32 v63, v56, 6, v133
	s_waitcnt lgkmcnt(1)
	v_sub_u32_e32 v149, s52, v58
	s_waitcnt vmcnt(12)
	v_mfma_f32_16x16x32_fp8_fp8 v[56:59], v[40:41], v[84:85], 0
	v_med3_i32 v40, v149, 0, s61
	v_cmp_lt_i32_e64 s[16:17], -1, v149
	v_lshl_add_u32 v149, v40, 6, v133
	v_mfma_f32_16x16x32_fp8_fp8 v[40:43], v[42:43], v[86:87], v[56:59]
	s_waitcnt lgkmcnt(0)
	v_sub_u32_e32 v61, s52, v61
	global_load_dwordx4 v[20:23], v28, s[44:45] offset:16
	s_nop 0
	global_load_dwordx4 v[28:31], v28, s[44:45]
	v_med3_i32 v56, v61, 0, s61
	v_mfma_f32_16x16x32_fp8_fp8 v[40:43], v[32:33], v[88:89], v[40:43]
	v_lshl_add_u32 v56, v56, 6, v133
	ds_read_b32 v56, v56
	ds_read_b32 v57, v149
	ds_read_b32 v58, v63
	ds_read_b32 v59, v62
	v_mfma_f32_16x16x32_fp8_fp8 v[32:35], v[34:35], v[90:91], v[40:43]
	s_sub_i32 s18, s63, 63
	v_cmp_gt_i32_e32 vcc, s18, v82
	s_waitcnt lgkmcnt(0)
	v_cmp_gt_i32_e64 s[10:11], s18, v140
	s_nop 3
	v_fmac_f32_e32 v59, 0x3e0293ee, v32
	s_and_b64 vcc, vcc, s[8:9]
	v_cmp_gt_i32_e64 s[14:15], s18, v141
	v_cndmask_b32_e32 v155, v103, v59, vcc
	v_fmac_f32_e32 v58, 0x3e0293ee, v33
	s_and_b64 vcc, s[10:11], s[12:13]
	v_cmp_gt_i32_e64 s[18:19], s18, v139
	v_cmp_lt_i32_e64 s[20:21], -1, v61
	v_cndmask_b32_e32 v156, v103, v58, vcc
	v_fmac_f32_e32 v57, 0x3e0293ee, v34
	s_and_b64 vcc, s[14:15], s[16:17]
	v_cndmask_b32_e32 v157, v103, v57, vcc
	v_fmac_f32_e32 v56, 0x3e0293ee, v35
	s_and_b64 vcc, s[18:19], s[20:21]
	v_cndmask_b32_e32 v158, v103, v56, vcc
	ds_bpermute_b32 v56, v138, v121
	ds_bpermute_b32 v57, v138, v121 offset:4
	ds_bpermute_b32 v58, v138, v121 offset:8
	ds_bpermute_b32 v61, v138, v121 offset:12
	v_lshl_add_u32 v40, v114, 7, v60
	s_waitcnt lgkmcnt(3)
	v_sub_u32_e32 v56, s52, v56
	v_cmp_lt_i32_e64 s[8:9], -1, v56
	v_med3_i32 v56, v56, 0, s61
	v_lshl_add_u32 v62, v56, 6, v133
	s_waitcnt lgkmcnt(2)
	v_sub_u32_e32 v56, s52, v57
	v_cmp_lt_i32_e64 s[12:13], -1, v56
	v_med3_i32 v56, v56, 0, s61
	v_lshl_add_u32 v63, v56, 6, v133
	s_waitcnt lgkmcnt(1)
	v_sub_u32_e32 v149, s52, v58
	s_waitcnt vmcnt(12)
	v_mfma_f32_16x16x32_fp8_fp8 v[56:59], v[44:45], v[84:85], 0
	v_med3_i32 v44, v149, 0, s61
	v_cmp_lt_i32_e64 s[16:17], -1, v149
	v_lshl_add_u32 v149, v44, 6, v133
	v_mfma_f32_16x16x32_fp8_fp8 v[44:47], v[46:47], v[86:87], v[56:59]
	s_waitcnt lgkmcnt(0)
	v_sub_u32_e32 v61, s52, v61
	global_load_dwordx4 v[32:35], v40, s[44:45] offset:16
	s_nop 0
	global_load_dwordx4 v[40:43], v40, s[44:45]
	v_med3_i32 v56, v61, 0, s61
	v_mfma_f32_16x16x32_fp8_fp8 v[44:47], v[36:37], v[88:89], v[44:47]
	v_lshl_add_u32 v56, v56, 6, v133
	ds_read_b32 v56, v56
	ds_read_b32 v57, v149
	ds_read_b32 v58, v63
	ds_read_b32 v59, v62
	v_mfma_f32_16x16x32_fp8_fp8 v[36:39], v[38:39], v[90:91], v[44:47]
	s_add_i32 s18, s63, 0xffffffb1
	v_cmp_gt_i32_e32 vcc, s18, v82
	s_waitcnt lgkmcnt(0)
	v_cmp_gt_i32_e64 s[10:11], s18, v140
	s_nop 3
	v_fmac_f32_e32 v59, 0x3e0293ee, v36
	s_and_b64 vcc, vcc, s[8:9]
	v_cmp_gt_i32_e64 s[14:15], s18, v141
	v_cndmask_b32_e32 v161, v103, v59, vcc
	v_fmac_f32_e32 v58, 0x3e0293ee, v37
	s_and_b64 vcc, s[10:11], s[12:13]
	v_cmp_gt_i32_e64 s[18:19], s18, v139
	v_cmp_lt_i32_e64 s[20:21], -1, v61
	v_cndmask_b32_e32 v162, v103, v58, vcc
	v_fmac_f32_e32 v57, 0x3e0293ee, v38
	s_and_b64 vcc, s[14:15], s[16:17]
	v_cndmask_b32_e32 v163, v103, v57, vcc
	v_fmac_f32_e32 v56, 0x3e0293ee, v39
	s_and_b64 vcc, s[18:19], s[20:21]
	v_cndmask_b32_e32 v164, v103, v56, vcc
	ds_bpermute_b32 v56, v138, v120
	ds_bpermute_b32 v57, v138, v120 offset:4
	ds_bpermute_b32 v58, v138, v120 offset:8
	ds_bpermute_b32 v61, v138, v120 offset:12
	v_lshl_add_u32 v44, v113, 7, v60
	s_waitcnt lgkmcnt(3)
	v_sub_u32_e32 v56, s52, v56
	v_cmp_lt_i32_e64 s[8:9], -1, v56
	v_med3_i32 v56, v56, 0, s61
	v_lshl_add_u32 v62, v56, 6, v133
	s_waitcnt lgkmcnt(2)
; #define A8_ISSUE_K(kt) do { const char* kr_ = (const char*)K8 + (unsigned)(R[kt] * 512 + kvh * 128 + 32 * g); ring[(2 * (kt)) & 15] = *(const v4u*)kr_; ring[(2 * (kt) + 1) & 15] = *(const v4u*)(kr_ + 16); } while (0)
; #define A8_ISSUE_V(hc) do { _Pragma("unroll") for (int q2_ = 0; q2_ < 4; ++q2_) { const int rid_ = __shfl(R[hc], 4 * q2_ + g); \
;         ring[(4 * (hc) + q2_) & 15] = *(const v4u*)((const char*)VB + (unsigned)(rid_ * 1024 + kvh * 256 + 16 * lr)); } } while (0)
; DI void attn_unit_f8(LAS unsigned char* vbuf  , const LAS float* lut2  , const long (&qf)[4], const int* idx, int cnt_, int qpos_, int kvh, const unsigned char* K8, const bf16* VB, bf16* orow, int lane_) {
;     ...
;     for (int i = 0; i < 16; ++i) {
;         asm volatile("" ::: "memory");
;         {
;             int kp4[4];
; #pragma unroll
;             for (int e = 0; e < 4; ++e) kp4[e] = __shfl(R[i], 4 * g + e);
;             f32x4 acc = (f32x4){0.f, 0.f, 0.f, 0.f};
; #pragma unroll
;             for (int s = 0; s < 4; ++s) { const v4u w = ring[(2 * i + (s >> 1)) & 15]; const unsigned long long ka = (s & 1) ? ((unsigned long long)w.w << 32 | w.z) : ((unsigned long long)w.y << 32 | w.x);
;                 acc = __builtin_amdgcn_mfma_f32_16x16x32_fp8_fp8((long)ka, qf[s], acc, 0, 0, 0); }
;             float bs[4]; bool okv[4];
; #pragma unroll
;             for (int e = 0; e < 4; ++e) { const int rel = qpos - kp4[e]; okv[e] = (4 * g + e < cnt - 16 * i) && rel >= 0; const int rc = rel > 128 ? 128 : (rel < 0 ? 0 : rel); bs[e] = lut2[rc * 16 + hcol]; }
;             asm volatile("" : "+v"(bs[0]), "+v"(bs[1]), "+v"(bs[2]), "+v"(bs[3]));
; #pragma unroll
;             for (int e = 0; e < 4; ++e) acc[e] = okv[e] ? acc[e] * (0.08838834764831845f * 1.4426950408889634f) + bs[e] : -3.0e38f;
;             lg[i] = acc;
;         }
;         if (i + 8 < 16) A8_ISSUE_K(i + 8);
;         else if ((i & 1) == 1) A8_ISSUE_V((i - 9) / 2);
	v_sub_u32_e32 v56, s52, v57
	v_cmp_lt_i32_e64 s[12:13], -1, v56
	v_med3_i32 v56, v56, 0, s61
	v_lshl_add_u32 v63, v56, 6, v133
	s_waitcnt lgkmcnt(1)
	v_sub_u32_e32 v149, s52, v58
	s_waitcnt vmcnt(12)
	v_mfma_f32_16x16x32_fp8_fp8 v[56:59], v[52:53], v[84:85], 0
	v_med3_i32 v52, v149, 0, s61
	v_cmp_lt_i32_e64 s[16:17], -1, v149
	v_lshl_add_u32 v149, v52, 6, v133
	v_mfma_f32_16x16x32_fp8_fp8 v[52:55], v[54:55], v[86:87], v[56:59]
	s_waitcnt lgkmcnt(0)
	v_sub_u32_e32 v61, s52, v61
	global_load_dwordx4 v[36:39], v44, s[44:45] offset:16
	s_nop 0
	global_load_dwordx4 v[44:47], v44, s[44:45]
	v_med3_i32 v56, v61, 0, s61
	v_mfma_f32_16x16x32_fp8_fp8 v[52:55], v[48:49], v[88:89], v[52:55]
	v_lshl_add_u32 v56, v56, 6, v133
	ds_read_b32 v56, v56
	ds_read_b32 v57, v149
	ds_read_b32 v58, v63
	ds_read_b32 v59, v62
	v_mfma_f32_16x16x32_fp8_fp8 v[48:51], v[50:51], v[90:91], v[52:55]
	s_add_i32 s18, s63, 0xffffffa1
	v_cmp_gt_i32_e32 vcc, s18, v82
	s_waitcnt lgkmcnt(0)
	v_cmp_gt_i32_e64 s[10:11], s18, v140
	s_nop 3
	v_fmac_f32_e32 v59, 0x3e0293ee, v48
	s_and_b64 vcc, vcc, s[8:9]
	v_cmp_gt_i32_e64 s[14:15], s18, v141
	v_cndmask_b32_e32 v167, v103, v59, vcc
	v_fmac_f32_e32 v58, 0x3e0293ee, v49
	s_and_b64 vcc, s[10:11], s[12:13]
	v_cmp_gt_i32_e64 s[18:19], s18, v139
	v_cmp_lt_i32_e64 s[20:21], -1, v61
	v_cndmask_b32_e32 v168, v103, v58, vcc
	v_fmac_f32_e32 v57, 0x3e0293ee, v50
	s_and_b64 vcc, s[14:15], s[16:17]
	v_cndmask_b32_e32 v169, v103, v57, vcc
	v_fmac_f32_e32 v56, 0x3e0293ee, v51
	s_and_b64 vcc, s[18:19], s[20:21]
	v_lshl_add_u32 v52, v112, 7, v60
	v_cndmask_b32_e32 v170, v103, v56, vcc
	global_load_dwordx4 v[48:51], v52, s[44:45] offset:16
	global_load_dwordx4 v[56:59], v52, s[44:45]
	ds_bpermute_b32 v52, v138, v118
	ds_bpermute_b32 v53, v138, v118 offset:4
	ds_bpermute_b32 v54, v138, v118 offset:8
	ds_bpermute_b32 v61, v138, v118 offset:12
	s_waitcnt lgkmcnt(3)
	v_sub_u32_e32 v52, s52, v52
	v_cmp_lt_i32_e64 s[8:9], -1, v52
	v_med3_i32 v52, v52, 0, s61
	v_lshl_add_u32 v62, v52, 6, v133
	s_waitcnt lgkmcnt(2)
	v_sub_u32_e32 v52, s52, v53
	v_cmp_lt_i32_e64 s[12:13], -1, v52
	v_med3_i32 v52, v52, 0, s61
	v_lshl_add_u32 v63, v52, 6, v133
	s_waitcnt lgkmcnt(1)
	v_sub_u32_e32 v149, s52, v54
	s_waitcnt vmcnt(14)
	v_mfma_f32_16x16x32_fp8_fp8 v[52:55], v[12:13], v[84:85], 0
	v_med3_i32 v12, v149, 0, s61
	v_cmp_lt_i32_e64 s[16:17], -1, v149
	v_lshl_add_u32 v149, v12, 6, v133
	v_mfma_f32_16x16x32_fp8_fp8 v[12:15], v[14:15], v[86:87], v[52:55]
	s_waitcnt lgkmcnt(0)
	v_sub_u32_e32 v61, s52, v61
	s_add_i32 s18, s63, 0xffffff91
	v_cmp_gt_i32_e32 vcc, s18, v82
	v_med3_i32 v52, v61, 0, s61
	v_mfma_f32_16x16x32_fp8_fp8 v[12:15], v[0:1], v[88:89], v[12:15]
	v_lshl_add_u32 v52, v52, 6, v133
	ds_read_b32 v52, v52
	ds_read_b32 v53, v149
	ds_read_b32 v54, v63
	ds_read_b32 v55, v62
	s_waitcnt lgkmcnt(0)
	v_mfma_f32_16x16x32_fp8_fp8 v[0:3], v[2:3], v[90:91], v[12:15]
	v_cmp_gt_i32_e64 s[10:11], s18, v140
	s_and_b64 vcc, vcc, s[8:9]
	v_cmp_gt_i32_e64 s[14:15], s18, v141
	v_cmp_gt_i32_e64 s[18:19], s18, v139
	v_cmp_lt_i32_e64 s[20:21], -1, v61
	s_nop 2
	v_fmac_f32_e32 v55, 0x3e0293ee, v0
	v_cndmask_b32_e32 v172, v103, v55, vcc
	v_fmac_f32_e32 v54, 0x3e0293ee, v1
	s_and_b64 vcc, s[10:11], s[12:13]
	v_cndmask_b32_e32 v173, v103, v54, vcc
	v_fmac_f32_e32 v53, 0x3e0293ee, v2
	s_and_b64 vcc, s[14:15], s[16:17]
	v_cndmask_b32_e32 v174, v103, v53, vcc
	v_fmac_f32_e32 v52, 0x3e0293ee, v3
	s_and_b64 vcc, s[18:19], s[20:21]
	v_lshl_add_u32 v0, v110, 7, v60
	v_cndmask_b32_e32 v175, v103, v52, vcc
	global_load_dwordx4 v[52:55], v0, s[44:45] offset:16
	global_load_dwordx4 v[60:63], v0, s[44:45]
	ds_bpermute_b32 v0, v138, v119
	ds_bpermute_b32 v1, v138, v119 offset:4
	ds_bpermute_b32 v2, v138, v119 offset:8
	ds_bpermute_b32 v12, v138, v119 offset:12
	s_waitcnt lgkmcnt(3)
	v_sub_u32_e32 v0, s52, v0
	v_cmp_lt_i32_e64 s[8:9], -1, v0
	v_med3_i32 v0, v0, 0, s61
	v_lshl_add_u32 v13, v0, 6, v133
	s_waitcnt lgkmcnt(2)
	v_sub_u32_e32 v0, s52, v1
	v_cmp_lt_i32_e64 s[12:13], -1, v0
	v_med3_i32 v0, v0, 0, s61
	v_lshl_add_u32 v14, v0, 6, v133
	s_waitcnt lgkmcnt(1)
	v_sub_u32_e32 v15, s52, v2
	s_waitcnt vmcnt(14)
	v_mfma_f32_16x16x32_fp8_fp8 v[0:3], v[64:65], v[84:85], 0
	s_waitcnt lgkmcnt(0)
	v_sub_u32_e32 v12, s52, v12
	v_med3_i32 v64, v12, 0, s61
	v_cmp_lt_i32_e64 s[16:17], -1, v15
	v_mfma_f32_16x16x32_fp8_fp8 v[0:3], v[66:67], v[86:87], v[0:3]
	v_med3_i32 v15, v15, 0, s61
	v_lshl_add_u32 v64, v64, 6, v133
	v_lshl_add_u32 v15, v15, 6, v133
	v_mfma_f32_16x16x32_fp8_fp8 v[0:3], v[4:5], v[88:89], v[0:3]
	ds_read_b32 v4, v64
	ds_read_b32 v5, v15
	ds_read_b32 v14, v14
	ds_read_b32 v13, v13
	s_waitcnt lgkmcnt(0)
	v_mfma_f32_16x16x32_fp8_fp8 v[0:3], v[6:7], v[90:91], v[0:3]
	s_add_i32 s18, s63, 0xffffff81
	v_cmp_gt_i32_e32 vcc, s18, v82
	v_cmp_gt_i32_e64 s[10:11], s18, v140
	s_and_b64 vcc, vcc, s[8:9]
	v_cmp_gt_i32_e64 s[14:15], s18, v141
	s_nop 2
	v_fmac_f32_e32 v13, 0x3e0293ee, v0
	ds_bpermute_b32 v0, v138, v117
	v_fmac_f32_e32 v14, 0x3e0293ee, v1
	ds_bpermute_b32 v1, v138, v117 offset:4
	v_fmac_f32_e32 v5, 0x3e0293ee, v2
	ds_bpermute_b32 v2, v138, v117 offset:8
	v_cndmask_b32_e32 v178, v103, v13, vcc
	s_and_b64 vcc, s[10:11], s[12:13]
	s_waitcnt lgkmcnt(2)
	v_sub_u32_e32 v0, s52, v0
	v_cndmask_b32_e32 v179, v103, v14, vcc
	s_and_b64 vcc, s[14:15], s[16:17]
	v_cmp_lt_i32_e64 s[8:9], -1, v0
	v_med3_i32 v0, v0, 0, s61
	v_cndmask_b32_e32 v181, v103, v5, vcc
	v_lshl_add_u32 v5, v0, 6, v133
	s_waitcnt lgkmcnt(1)
	v_sub_u32_e32 v0, s52, v1
	v_cmp_lt_i32_e64 s[12:13], -1, v0
	v_med3_i32 v0, v0, 0, s61
	v_cmp_gt_i32_e64 s[18:19], s18, v139
	v_cmp_lt_i32_e64 s[20:21], -1, v12
	v_fmac_f32_e32 v4, 0x3e0293ee, v3
	v_lshl_add_u32 v6, v0, 6, v133
	s_waitcnt lgkmcnt(0)
; #define A8_ISSUE_K(kt) do { const char* kr_ = (const char*)K8 + (unsigned)(R[kt] * 512 + kvh * 128 + 32 * g); ring[(2 * (kt)) & 15] = *(const v4u*)kr_; ring[(2 * (kt) + 1) & 15] = *(const v4u*)(kr_ + 16); } while (0)
; #define A8_ISSUE_V(hc) do { _Pragma("unroll") for (int q2_ = 0; q2_ < 4; ++q2_) { const int rid_ = __shfl(R[hc], 4 * q2_ + g); \
;         ring[(4 * (hc) + q2_) & 15] = *(const v4u*)((const char*)VB + (unsigned)(rid_ * 1024 + kvh * 256 + 16 * lr)); } } while (0)
; DI void attn_unit_f8(LAS unsigned char* vbuf  , const LAS float* lut2  , const long (&qf)[4], const int* idx, int cnt_, int qpos_, int kvh, const unsigned char* K8, const bf16* VB, bf16* orow, int lane_) {
;     ...
;     for (int i = 0; i < 16; ++i) {
;         asm volatile("" ::: "memory");
;         {
;             int kp4[4];
; #pragma unroll
;             for (int e = 0; e < 4; ++e) kp4[e] = __shfl(R[i], 4 * g + e);
;             f32x4 acc = (f32x4){0.f, 0.f, 0.f, 0.f};
; #pragma unroll
;             for (int s = 0; s < 4; ++s) { const v4u w = ring[(2 * i + (s >> 1)) & 15]; const unsigned long long ka = (s & 1) ? ((unsigned long long)w.w << 32 | w.z) : ((unsigned long long)w.y << 32 | w.x);
;                 acc = __builtin_amdgcn_mfma_f32_16x16x32_fp8_fp8((long)ka, qf[s], acc, 0, 0, 0); }
;             float bs[4]; bool okv[4];
; #pragma unroll
;             for (int e = 0; e < 4; ++e) { const int rel = qpos - kp4[e]; okv[e] = (4 * g + e < cnt - 16 * i) && rel >= 0; const int rc = rel > 128 ? 128 : (rel < 0 ? 0 : rel); bs[e] = lut2[rc * 16 + hcol]; }
;             asm volatile("" : "+v"(bs[0]), "+v"(bs[1]), "+v"(bs[2]), "+v"(bs[3]));
; #pragma unroll
;             for (int e = 0; e < 4; ++e) acc[e] = okv[e] ? acc[e] * (0.08838834764831845f * 1.4426950408889634f) + bs[e] : -3.0e38f;
;             lg[i] = acc;
;         }
;         if (i + 8 < 16) A8_ISSUE_K(i + 8);
;         else if ((i & 1) == 1) A8_ISSUE_V((i - 9) / 2);
	v_sub_u32_e32 v7, s52, v2
	s_waitcnt vmcnt(12)
	v_mfma_f32_16x16x32_fp8_fp8 v[0:3], v[68:69], v[84:85], 0
	s_and_b64 vcc, s[18:19], s[20:21]
	v_cndmask_b32_e32 v182, v103, v4, vcc
	ds_bpermute_b32 v4, v138, v117 offset:12
	v_mfma_f32_16x16x32_fp8_fp8 v[0:3], v[70:71], v[86:87], v[0:3]
	v_cmp_lt_i32_e64 s[16:17], -1, v7
	v_med3_i32 v7, v7, 0, s61
	s_waitcnt lgkmcnt(0)
	v_sub_u32_e32 v4, s52, v4
	v_med3_i32 v12, v4, 0, s61
	v_mfma_f32_16x16x32_fp8_fp8 v[0:3], v[8:9], v[88:89], v[0:3]
	v_lshl_add_u32 v7, v7, 6, v133
	v_lshl_add_u32 v12, v12, 6, v133
	ds_bpermute_b32 v68, v138, v116
	ds_read_b32 v8, v12
	ds_read_b32 v7, v7
	ds_read_b32 v6, v6
	ds_read_b32 v5, v5
	ds_bpermute_b32 v69, v138, v116 offset:4
	v_mfma_f32_16x16x32_fp8_fp8 v[0:3], v[10:11], v[90:91], v[0:3]
	s_add_i32 s18, s63, 0xffffff71
	ds_bpermute_b32 v70, v138, v116 offset:8
	v_cmp_gt_i32_e32 vcc, s18, v82
	s_waitcnt lgkmcnt(6)
	v_sub_u32_e32 v68, s52, v68
	s_waitcnt lgkmcnt(2)
	s_and_b64 vcc, vcc, s[8:9]
	v_cmp_lt_i32_e64 s[8:9], -1, v68
	v_med3_i32 v68, v68, 0, s61
	v_cmp_gt_i32_e64 s[10:11], s18, v140
	v_fmac_f32_e32 v5, 0x3e0293ee, v0
	v_fmac_f32_e32 v6, 0x3e0293ee, v1
	v_fmac_f32_e32 v7, 0x3e0293ee, v2
	v_and_or_b32 v0, v148, 63, v101
	v_fmac_f32_e32 v8, 0x3e0293ee, v3
	v_add_u32_e32 v1, 4, v148
	v_add_u32_e32 v2, 8, v148
	v_add_u32_e32 v3, 12, v148
	v_lshl_add_u32 v148, v68, 6, v133
	s_waitcnt lgkmcnt(1)
	v_sub_u32_e32 v68, s52, v69
	v_cndmask_b32_e32 v184, v103, v5, vcc
	s_and_b64 vcc, s[10:11], s[12:13]
	v_cmp_lt_i32_e64 s[12:13], -1, v68
	v_med3_i32 v68, v68, 0, s61
	v_and_or_b32 v1, v1, 63, v101
	v_and_or_b32 v2, v2, 63, v101
	v_and_or_b32 v3, v3, 63, v101
	v_lshl_add_u32 v149, v68, 6, v133
	s_waitcnt lgkmcnt(0)
	v_sub_u32_e32 v154, s52, v70
	s_waitcnt vmcnt(10)
	v_mfma_f32_16x16x32_fp8_fp8 v[68:71], v[24:25], v[84:85], 0
	v_lshlrev_b32_e32 v64, 2, v0
	v_lshlrev_b32_e32 v65, 2, v1
	v_lshlrev_b32_e32 v66, 2, v2
	v_lshlrev_b32_e32 v67, 2, v3
	ds_bpermute_b32 v0, v64, v147
	ds_bpermute_b32 v1, v65, v147
	ds_bpermute_b32 v2, v66, v147
	ds_bpermute_b32 v3, v67, v147
	ds_bpermute_b32 v147, v138, v116 offset:12
	v_cmp_gt_i32_e64 s[14:15], s18, v141
	v_med3_i32 v24, v154, 0, s61
	v_cndmask_b32_e32 v185, v103, v6, vcc
	s_and_b64 vcc, s[14:15], s[16:17]
	v_cmp_lt_i32_e64 s[16:17], -1, v154
	v_lshl_add_u32 v154, v24, 6, v133
	v_mfma_f32_16x16x32_fp8_fp8 v[24:27], v[26:27], v[86:87], v[68:71]
	v_cmp_gt_i32_e64 s[18:19], s18, v139
	v_cmp_lt_i32_e64 s[20:21], -1, v4
	s_waitcnt lgkmcnt(4)
	v_lshl_or_b32 v0, v0, 10, v111
	s_waitcnt lgkmcnt(3)
	v_lshl_or_b32 v1, v1, 10, v111
	s_waitcnt lgkmcnt(0)
	v_sub_u32_e32 v147, s52, v147
	v_cndmask_b32_e32 v186, v103, v7, vcc
	s_and_b64 vcc, s[18:19], s[20:21]
	global_load_dwordx4 v[12:15], v0, s[46:47]
	global_load_dwordx4 v[4:7], v1, s[46:47]
	v_lshl_or_b32 v0, v2, 10, v111
	v_lshl_or_b32 v1, v3, 10, v111
	v_med3_i32 v68, v147, 0, s61
	v_mfma_f32_16x16x32_fp8_fp8 v[24:27], v[16:17], v[88:89], v[24:27]
	v_cndmask_b32_e32 v187, v103, v8, vcc
	global_load_dwordx4 v[8:11], v0, s[46:47]
	s_nop 0
	global_load_dwordx4 v[0:3], v1, s[46:47]
	v_lshl_add_u32 v68, v68, 6, v133
	ds_read_b32 v68, v68
	ds_read_b32 v69, v154
	ds_read_b32 v70, v149
	ds_read_b32 v71, v148
	v_mfma_f32_16x16x32_fp8_fp8 v[16:19], v[18:19], v[90:91], v[24:27]
	s_waitcnt lgkmcnt(0)
	s_add_i32 s18, s63, 0xffffff61
	s_nop 5
	v_fmac_f32_e32 v71, 0x3e0293ee, v16
	ds_bpermute_b32 v16, v138, v115
	v_fmac_f32_e32 v70, 0x3e0293ee, v17
	ds_bpermute_b32 v17, v138, v115 offset:4
	v_fmac_f32_e32 v69, 0x3e0293ee, v18
	ds_bpermute_b32 v18, v138, v115 offset:8
	v_cmp_gt_i32_e32 vcc, s18, v82
	s_waitcnt lgkmcnt(2)
	v_sub_u32_e32 v16, s52, v16
	s_and_b64 vcc, vcc, s[8:9]
	v_cmp_lt_i32_e64 s[8:9], -1, v16
	v_med3_i32 v16, v16, 0, s61
	v_cmp_gt_i32_e64 s[10:11], s18, v140
	v_lshl_add_u32 v25, v16, 6, v133
	s_waitcnt lgkmcnt(1)
	v_sub_u32_e32 v16, s52, v17
	v_cndmask_b32_e32 v188, v103, v71, vcc
	s_and_b64 vcc, s[10:11], s[12:13]
	v_cmp_lt_i32_e64 s[12:13], -1, v16
	v_med3_i32 v16, v16, 0, s61
	v_fmac_f32_e32 v68, 0x3e0293ee, v19
	v_lshl_add_u32 v26, v16, 6, v133
	s_waitcnt lgkmcnt(0)
	v_sub_u32_e32 v27, s52, v18
	s_waitcnt vmcnt(12)
	v_mfma_f32_16x16x32_fp8_fp8 v[16:19], v[28:29], v[84:85], 0
	ds_bpermute_b32 v24, v138, v115 offset:12
	v_cmp_gt_i32_e64 s[14:15], s18, v141
	v_cmp_gt_i32_e64 s[18:19], s18, v139
	v_mfma_f32_16x16x32_fp8_fp8 v[16:19], v[30:31], v[86:87], v[16:19]
	v_cmp_lt_i32_e64 s[20:21], -1, v147
	v_cndmask_b32_e32 v189, v103, v70, vcc
	s_and_b64 vcc, s[14:15], s[16:17]
	s_waitcnt lgkmcnt(0)
	v_sub_u32_e32 v24, s52, v24
	v_cndmask_b32_e32 v190, v103, v69, vcc
	s_and_b64 vcc, s[18:19], s[20:21]
	v_med3_i32 v28, v24, 0, s61
	v_mfma_f32_16x16x32_fp8_fp8 v[16:19], v[20:21], v[88:89], v[16:19]
	v_cndmask_b32_e32 v191, v103, v68, vcc
	v_cmp_lt_i32_e64 s[16:17], -1, v27
	v_med3_i32 v27, v27, 0, s61
	v_lshl_add_u32 v28, v28, 6, v133
	ds_bpermute_b32 v68, v138, v114
	v_lshl_add_u32 v27, v27, 6, v133
	ds_read_b32 v20, v28
	ds_read_b32 v21, v27
	ds_read_b32 v26, v26
	ds_read_b32 v25, v25
	ds_bpermute_b32 v69, v138, v114 offset:4
	v_mfma_f32_16x16x32_fp8_fp8 v[16:19], v[22:23], v[90:91], v[16:19]
	s_add_i32 s18, s63, 0xffffff51
	ds_bpermute_b32 v70, v138, v114 offset:8
	v_cmp_gt_i32_e32 vcc, s18, v82
	s_waitcnt lgkmcnt(6)
	v_sub_u32_e32 v68, s52, v68
	s_waitcnt lgkmcnt(2)
	s_and_b64 vcc, vcc, s[8:9]
	v_cmp_lt_i32_e64 s[8:9], -1, v68
	v_med3_i32 v68, v68, 0, s61
	v_cmp_gt_i32_e64 s[10:11], s18, v140
	v_fmac_f32_e32 v25, 0x3e0293ee, v16
	v_lshl_add_u32 v147, v68, 6, v133
	s_waitcnt lgkmcnt(1)
; #define A8_ISSUE_K(kt) do { const char* kr_ = (const char*)K8 + (unsigned)(R[kt] * 512 + kvh * 128 + 32 * g); ring[(2 * (kt)) & 15] = *(const v4u*)kr_; ring[(2 * (kt) + 1) & 15] = *(const v4u*)(kr_ + 16); } while (0)
; #define A8_ISSUE_V(hc) do { _Pragma("unroll") for (int q2_ = 0; q2_ < 4; ++q2_) { const int rid_ = __shfl(R[hc], 4 * q2_ + g); \
;         ring[(4 * (hc) + q2_) & 15] = *(const v4u*)((const char*)VB + (unsigned)(rid_ * 1024 + kvh * 256 + 16 * lr)); } } while (0)
; DI void attn_unit_f8(LAS unsigned char* vbuf  , const LAS float* lut2  , const long (&qf)[4], const int* idx, int cnt_, int qpos_, int kvh, const unsigned char* K8, const bf16* VB, bf16* orow, int lane_) {
;     ...
;     for (int i = 0; i < 16; ++i) {
;         asm volatile("" ::: "memory");
;         {
;             int kp4[4];
; #pragma unroll
;             for (int e = 0; e < 4; ++e) kp4[e] = __shfl(R[i], 4 * g + e);
;             f32x4 acc = (f32x4){0.f, 0.f, 0.f, 0.f};
; #pragma unroll
;             for (int s = 0; s < 4; ++s) { const v4u w = ring[(2 * i + (s >> 1)) & 15]; const unsigned long long ka = (s & 1) ? ((unsigned long long)w.w << 32 | w.z) : ((unsigned long long)w.y << 32 | w.x);
;                 acc = __builtin_amdgcn_mfma_f32_16x16x32_fp8_fp8((long)ka, qf[s], acc, 0, 0, 0); }
;             float bs[4]; bool okv[4];
; #pragma unroll
;             for (int e = 0; e < 4; ++e) { const int rel = qpos - kp4[e]; okv[e] = (4 * g + e < cnt - 16 * i) && rel >= 0; const int rc = rel > 128 ? 128 : (rel < 0 ? 0 : rel); bs[e] = lut2[rc * 16 + hcol]; }
;             asm volatile("" : "+v"(bs[0]), "+v"(bs[1]), "+v"(bs[2]), "+v"(bs[3]));
; #pragma unroll
;             for (int e = 0; e < 4; ++e) acc[e] = okv[e] ? acc[e] * (0.08838834764831845f * 1.4426950408889634f) + bs[e] : -3.0e38f;
;             lg[i] = acc;
;         }
;         if (i + 8 < 16) A8_ISSUE_K(i + 8);
;         else if ((i & 1) == 1) A8_ISSUE_V((i - 9) / 2);
	v_sub_u32_e32 v68, s52, v69
	v_cndmask_b32_e32 v192, v103, v25, vcc
	s_and_b64 vcc, s[10:11], s[12:13]
	v_cmp_lt_i32_e64 s[12:13], -1, v68
	v_med3_i32 v68, v68, 0, s61
	v_lshl_add_u32 v148, v68, 6, v133
	s_waitcnt lgkmcnt(0)
	v_sub_u32_e32 v149, s52, v70
	s_waitcnt vmcnt(10)
	v_mfma_f32_16x16x32_fp8_fp8 v[68:71], v[40:41], v[84:85], 0
	v_cmp_lt_i32_e64 s[20:21], -1, v24
	v_fmac_f32_e32 v26, 0x3e0293ee, v17
	ds_bpermute_b32 v16, v64, v142
	ds_bpermute_b32 v17, v65, v142
	ds_bpermute_b32 v24, v66, v142
	ds_bpermute_b32 v25, v67, v142
	ds_bpermute_b32 v142, v138, v114 offset:12
	v_cmp_gt_i32_e64 s[14:15], s18, v141
	v_med3_i32 v40, v149, 0, s61
	v_cndmask_b32_e32 v183, v103, v26, vcc
	s_and_b64 vcc, s[14:15], s[16:17]
	v_cmp_lt_i32_e64 s[16:17], -1, v149
	v_lshl_add_u32 v149, v40, 6, v133
	v_mfma_f32_16x16x32_fp8_fp8 v[40:43], v[42:43], v[86:87], v[68:71]
	v_cmp_gt_i32_e64 s[18:19], s18, v139
	v_fmac_f32_e32 v21, 0x3e0293ee, v18
	s_waitcnt lgkmcnt(0)
	v_sub_u32_e32 v142, s52, v142
	v_cndmask_b32_e32 v180, v103, v21, vcc
	v_fmac_f32_e32 v20, 0x3e0293ee, v19
	s_and_b64 vcc, s[18:19], s[20:21]
	v_lshl_or_b32 v16, v16, 10, v111
	v_lshl_or_b32 v17, v17, 10, v111
	v_lshl_or_b32 v24, v24, 10, v111
	v_lshl_or_b32 v28, v25, 10, v111
	v_med3_i32 v68, v142, 0, s61
	v_mfma_f32_16x16x32_fp8_fp8 v[40:43], v[32:33], v[88:89], v[40:43]
	v_cndmask_b32_e32 v171, v103, v20, vcc
	global_load_dwordx4 v[20:23], v16, s[46:47]
	s_nop 0
	global_load_dwordx4 v[16:19], v17, s[46:47]
	s_nop 0
	global_load_dwordx4 v[24:27], v24, s[46:47]
	s_nop 0
	global_load_dwordx4 v[28:31], v28, s[46:47]
	v_lshl_add_u32 v68, v68, 6, v133
	ds_read_b32 v68, v68
	ds_read_b32 v69, v149
	ds_read_b32 v70, v148
	ds_read_b32 v71, v147
	v_mfma_f32_16x16x32_fp8_fp8 v[32:35], v[34:35], v[90:91], v[40:43]
	s_waitcnt lgkmcnt(0)
	s_add_i32 s18, s63, 0xffffff41
	s_nop 5
	v_fmac_f32_e32 v71, 0x3e0293ee, v32
	ds_bpermute_b32 v32, v138, v113
	v_fmac_f32_e32 v70, 0x3e0293ee, v33
	ds_bpermute_b32 v33, v138, v113 offset:4
	v_fmac_f32_e32 v69, 0x3e0293ee, v34
	ds_bpermute_b32 v34, v138, v113 offset:8
	v_cmp_gt_i32_e32 vcc, s18, v82
	s_waitcnt lgkmcnt(2)
	v_sub_u32_e32 v32, s52, v32
	s_and_b64 vcc, vcc, s[8:9]
	v_cmp_lt_i32_e64 s[8:9], -1, v32
	v_med3_i32 v32, v32, 0, s61
	v_cmp_gt_i32_e64 s[10:11], s18, v140
	v_lshl_add_u32 v41, v32, 6, v133
	s_waitcnt lgkmcnt(1)
	v_sub_u32_e32 v32, s52, v33
	v_cndmask_b32_e32 v177, v103, v71, vcc
	s_and_b64 vcc, s[10:11], s[12:13]
	v_cmp_lt_i32_e64 s[12:13], -1, v32
	v_med3_i32 v32, v32, 0, s61
	v_fmac_f32_e32 v68, 0x3e0293ee, v35
	v_lshl_add_u32 v42, v32, 6, v133
	s_waitcnt lgkmcnt(0)
	v_sub_u32_e32 v43, s52, v34
	s_waitcnt vmcnt(12)
	v_mfma_f32_16x16x32_fp8_fp8 v[32:35], v[44:45], v[84:85], 0
	ds_bpermute_b32 v40, v138, v113 offset:12
	v_cmp_gt_i32_e64 s[14:15], s18, v141
	v_cmp_gt_i32_e64 s[18:19], s18, v139
	v_mfma_f32_16x16x32_fp8_fp8 v[32:35], v[46:47], v[86:87], v[32:35]
	v_cmp_lt_i32_e64 s[20:21], -1, v142
	v_cndmask_b32_e32 v176, v103, v70, vcc
	s_and_b64 vcc, s[14:15], s[16:17]
	s_waitcnt lgkmcnt(0)
	v_sub_u32_e32 v40, s52, v40
	v_cndmask_b32_e32 v166, v103, v69, vcc
	s_and_b64 vcc, s[18:19], s[20:21]
	v_med3_i32 v44, v40, 0, s61
	v_mfma_f32_16x16x32_fp8_fp8 v[32:35], v[36:37], v[88:89], v[32:35]
	v_cndmask_b32_e32 v165, v103, v68, vcc
	v_cmp_lt_i32_e64 s[16:17], -1, v43
	v_med3_i32 v43, v43, 0, s61
	v_lshl_add_u32 v44, v44, 6, v133
	ds_bpermute_b32 v68, v138, v112
	v_lshl_add_u32 v43, v43, 6, v133
	ds_read_b32 v36, v44
	ds_read_b32 v37, v43
	ds_read_b32 v42, v42
	ds_read_b32 v41, v41
	ds_bpermute_b32 v69, v138, v112 offset:4
	v_mfma_f32_16x16x32_fp8_fp8 v[32:35], v[38:39], v[90:91], v[32:35]
	s_add_i32 s18, s63, 0xffffff31
	ds_bpermute_b32 v70, v138, v112 offset:8
	v_cmp_gt_i32_e32 vcc, s18, v82
	s_waitcnt lgkmcnt(6)
	v_sub_u32_e32 v68, s52, v68
	s_waitcnt lgkmcnt(2)
	s_and_b64 vcc, vcc, s[8:9]
	v_cmp_lt_i32_e64 s[8:9], -1, v68
	v_med3_i32 v68, v68, 0, s61
	v_cmp_gt_i32_e64 s[10:11], s18, v140
	v_fmac_f32_e32 v41, 0x3e0293ee, v32
	v_lshl_add_u32 v142, v68, 6, v133
	s_waitcnt lgkmcnt(1)
	v_sub_u32_e32 v68, s52, v69
	v_cndmask_b32_e32 v160, v103, v41, vcc
	s_and_b64 vcc, s[10:11], s[12:13]
	v_cmp_lt_i32_e64 s[12:13], -1, v68
	v_med3_i32 v68, v68, 0, s61
	v_lshl_add_u32 v147, v68, 6, v133
	s_waitcnt lgkmcnt(0)
	v_sub_u32_e32 v154, s52, v70
	s_waitcnt vmcnt(10)
	v_mfma_f32_16x16x32_fp8_fp8 v[68:71], v[56:57], v[84:85], 0
	v_fmac_f32_e32 v42, 0x3e0293ee, v33
	v_fmac_f32_e32 v37, 0x3e0293ee, v34
	ds_bpermute_b32 v32, v64, v132
	v_fmac_f32_e32 v36, 0x3e0293ee, v35
	ds_bpermute_b32 v33, v65, v132
	ds_bpermute_b32 v34, v66, v132
	ds_bpermute_b32 v35, v67, v132
	ds_bpermute_b32 v132, v138, v112 offset:12
	v_cmp_gt_i32_e64 s[14:15], s18, v141
	v_med3_i32 v56, v154, 0, s61
	v_cndmask_b32_e32 v159, v103, v42, vcc
	s_and_b64 vcc, s[14:15], s[16:17]
	v_cmp_lt_i32_e64 s[16:17], -1, v154
	v_lshl_add_u32 v154, v56, 6, v133
	v_mfma_f32_16x16x32_fp8_fp8 v[56:59], v[58:59], v[86:87], v[68:71]
	v_cmp_gt_i32_e64 s[18:19], s18, v139
	v_cmp_lt_i32_e64 s[20:21], -1, v40
	v_cndmask_b32_e32 v149, v103, v37, vcc
	s_and_b64 vcc, s[18:19], s[20:21]
	s_waitcnt lgkmcnt(4)
	v_lshl_or_b32 v32, v32, 10, v111
	s_waitcnt lgkmcnt(3)
	v_lshl_or_b32 v33, v33, 10, v111
	s_waitcnt lgkmcnt(0)
	v_sub_u32_e32 v132, s52, v132
	v_cndmask_b32_e32 v148, v103, v36, vcc
	global_load_dwordx4 v[44:47], v32, s[46:47]
	global_load_dwordx4 v[36:39], v33, s[46:47]
	v_lshl_or_b32 v32, v34, 10, v111
	v_lshl_or_b32 v33, v35, 10, v111
	v_med3_i32 v68, v132, 0, s61
	v_mfma_f32_16x16x32_fp8_fp8 v[56:59], v[48:49], v[88:89], v[56:59]
	global_load_dwordx4 v[40:43], v32, s[46:47]
	s_nop 0
	global_load_dwordx4 v[32:35], v33, s[46:47]
	v_lshl_add_u32 v68, v68, 6, v133
	ds_read_b32 v68, v68
	ds_read_b32 v69, v154
	ds_read_b32 v70, v147
	ds_read_b32 v71, v142
	v_mfma_f32_16x16x32_fp8_fp8 v[48:51], v[50:51], v[90:91], v[56:59]
	s_waitcnt lgkmcnt(0)
; #define A8_ISSUE_K(kt) do { const char* kr_ = (const char*)K8 + (unsigned)(R[kt] * 512 + kvh * 128 + 32 * g); ring[(2 * (kt)) & 15] = *(const v4u*)kr_; ring[(2 * (kt) + 1) & 15] = *(const v4u*)(kr_ + 16); } while (0)
; #define A8_ISSUE_V(hc) do { _Pragma("unroll") for (int q2_ = 0; q2_ < 4; ++q2_) { const int rid_ = __shfl(R[hc], 4 * q2_ + g); \
;         ring[(4 * (hc) + q2_) & 15] = *(const v4u*)((const char*)VB + (unsigned)(rid_ * 1024 + kvh * 256 + 16 * lr)); } } while (0)
; DI void attn_unit_f8(LAS unsigned char* vbuf  , const LAS float* lut2  , const long (&qf)[4], const int* idx, int cnt_, int qpos_, int kvh, const unsigned char* K8, const bf16* VB, bf16* orow, int lane_) {
;     ...
;             for (int e = 0; e < 4; ++e) { const int rel = qpos - kp4[e]; okv[e] = (4 * g + e < cnt - 16 * i) && rel >= 0; const int rc = rel > 128 ? 128 : (rel < 0 ? 0 : rel); bs[e] = lut2[rc * 16 + hcol]; }
;             asm volatile("" : "+v"(bs[0]), "+v"(bs[1]), "+v"(bs[2]), "+v"(bs[3]));
; #pragma unroll
;             for (int e = 0; e < 4; ++e) acc[e] = okv[e] ? acc[e] * (0.08838834764831845f * 1.4426950408889634f) + bs[e] : -3.0e38f;
;             lg[i] = acc;
;         }
;         if (i + 8 < 16) A8_ISSUE_K(i + 8);
;         else if ((i & 1) == 1) A8_ISSUE_V((i - 9) / 2);
;     }
;     {
;         float mx = -3.0e38f;
; #pragma unroll
;         for (int kt = 0; kt < 16; ++kt) mx = fmaxf(fmaxf(fmaxf(lg[kt][0], lg[kt][1]), fmaxf(lg[kt][2], lg[kt][3])), mx);
;         mx = fmaxf(mx, __shfl_xor(mx, 16)); mx = fmaxf(mx, __shfl_xor(mx, 32));
	s_add_i32 s18, s63, 0xffffff21
	s_nop 5
	v_fmac_f32_e32 v71, 0x3e0293ee, v48
	ds_bpermute_b32 v48, v138, v110
	v_fmac_f32_e32 v70, 0x3e0293ee, v49
	ds_bpermute_b32 v49, v138, v110 offset:4
	v_fmac_f32_e32 v69, 0x3e0293ee, v50
	ds_bpermute_b32 v50, v138, v110 offset:8
	v_cmp_gt_i32_e32 vcc, s18, v82
	s_waitcnt lgkmcnt(2)
	v_sub_u32_e32 v48, s52, v48
	s_and_b64 vcc, vcc, s[8:9]
	v_cmp_lt_i32_e64 s[8:9], -1, v48
	v_med3_i32 v48, v48, 0, s61
	v_cmp_gt_i32_e64 s[10:11], s18, v140
	v_lshl_add_u32 v57, v48, 6, v133
	s_waitcnt lgkmcnt(1)
	v_sub_u32_e32 v48, s52, v49
	v_cndmask_b32_e32 v154, v103, v71, vcc
	s_and_b64 vcc, s[10:11], s[12:13]
	v_cmp_lt_i32_e64 s[12:13], -1, v48
	v_med3_i32 v48, v48, 0, s61
	v_fmac_f32_e32 v68, 0x3e0293ee, v51
	v_lshl_add_u32 v58, v48, 6, v133
	s_waitcnt lgkmcnt(0)
	v_sub_u32_e32 v59, s52, v50
	s_waitcnt vmcnt(12)
	v_mfma_f32_16x16x32_fp8_fp8 v[48:51], v[60:61], v[84:85], 0
	ds_bpermute_b32 v56, v138, v110 offset:12
	v_cmp_gt_i32_e64 s[14:15], s18, v141
	v_cndmask_b32_e32 v147, v103, v70, vcc
	v_mfma_f32_16x16x32_fp8_fp8 v[48:51], v[62:63], v[86:87], v[48:51]
	s_and_b64 vcc, s[14:15], s[16:17]
	s_waitcnt lgkmcnt(0)
	v_sub_u32_e32 v56, s52, v56
	v_med3_i32 v60, v56, 0, s61
	v_mfma_f32_16x16x32_fp8_fp8 v[48:51], v[52:53], v[88:89], v[48:51]
	v_cmp_lt_i32_e64 s[16:17], -1, v59
	v_med3_i32 v59, v59, 0, s61
	v_lshl_add_u32 v60, v60, 6, v133
	v_lshl_add_u32 v59, v59, 6, v133
	ds_read_b32 v52, v60
	ds_read_b32 v53, v59
	ds_read_b32 v58, v58
	ds_read_b32 v57, v57
	v_mfma_f32_16x16x32_fp8_fp8 v[48:51], v[54:55], v[90:91], v[48:51]
	v_cmp_gt_i32_e64 s[18:19], s18, v139
	v_cmp_lt_i32_e64 s[20:21], -1, v132
	v_cndmask_b32_e32 v132, v103, v69, vcc
	s_and_b64 vcc, s[18:19], s[20:21]
	s_addk_i32 s63, 0xff11
	v_cndmask_b32_e32 v142, v103, v68, vcc
	v_cmp_gt_i32_e32 vcc, s63, v82
	s_waitcnt lgkmcnt(0)
	v_cmp_gt_i32_e64 s[10:11], s63, v140
	v_fmac_f32_e32 v57, 0x3e0293ee, v48
	s_and_b64 vcc, vcc, s[8:9]
	v_cmp_gt_i32_e64 s[14:15], s63, v141
	v_cndmask_b32_e32 v71, v103, v57, vcc
	v_fmac_f32_e32 v58, 0x3e0293ee, v49
	s_and_b64 vcc, s[10:11], s[12:13]
	v_cmp_gt_i32_e64 s[18:19], s63, v139
	v_cmp_lt_i32_e64 s[20:21], -1, v56
	v_cndmask_b32_e32 v84, v103, v58, vcc
	v_fmac_f32_e32 v53, 0x3e0293ee, v50
	s_and_b64 vcc, s[14:15], s[16:17]
	v_cndmask_b32_e32 v70, v103, v53, vcc
	v_fmac_f32_e32 v52, 0x3e0293ee, v51
	s_and_b64 vcc, s[18:19], s[20:21]
	v_max_f32_e32 v50, v128, v129
	v_max_f32_e32 v51, v130, v131
	v_cndmask_b32_e32 v69, v103, v52, vcc
	v_max3_f32 v50, v50, v51, s62
	v_max_f32_e32 v51, v134, v135
	v_max_f32_e32 v52, v136, v137
	v_max3_f32 v50, v51, v52, v50
	v_max_f32_e32 v51, v143, v144
	v_max_f32_e32 v52, v145, v146
	v_max3_f32 v50, v51, v52, v50
	v_max_f32_e32 v51, v150, v151
	v_max_f32_e32 v52, v152, v153
	v_max3_f32 v50, v51, v52, v50
	v_max_f32_e32 v51, v155, v156
	v_max_f32_e32 v52, v157, v158
	v_max3_f32 v50, v51, v52, v50
	v_max_f32_e32 v51, v161, v162
	v_max_f32_e32 v52, v163, v164
	v_max3_f32 v50, v51, v52, v50
	v_max_f32_e32 v51, v167, v168
	v_max_f32_e32 v52, v169, v170
	v_max3_f32 v50, v51, v52, v50
	v_max_f32_e32 v51, v172, v173
	v_max_f32_e32 v52, v174, v175
	v_max3_f32 v50, v51, v52, v50
	v_max_f32_e32 v51, v178, v179
	v_max_f32_e32 v52, v181, v182
	v_max3_f32 v50, v51, v52, v50
	v_max_f32_e32 v51, v184, v185
	v_max_f32_e32 v52, v186, v187
	v_max3_f32 v50, v51, v52, v50
	v_max_f32_e32 v51, v188, v189
	v_max_f32_e32 v52, v190, v191
	v_max3_f32 v50, v51, v52, v50
	v_max_f32_e32 v51, v192, v183
	v_max_f32_e32 v52, v180, v171
	v_max3_f32 v50, v51, v52, v50
	v_max_f32_e32 v51, v177, v176
	v_max_f32_e32 v52, v166, v165
	v_max3_f32 v50, v51, v52, v50
	v_max_f32_e32 v51, v160, v159
	v_max_f32_e32 v52, v149, v148
	v_max3_f32 v50, v51, v52, v50
	v_max_f32_e32 v51, v154, v147
	v_max_f32_e32 v52, v132, v142
	v_max3_f32 v50, v51, v52, v50
	v_max_f32_e32 v51, v71, v84
	v_max_f32_e32 v52, v70, v69
	v_max3_f32 v57, v51, v52, v50
	ds_bpermute_b32 v58, v72, v57
	ds_bpermute_b32 v48, v64, v125
	ds_bpermute_b32 v49, v65, v125
	ds_bpermute_b32 v56, v66, v125
	ds_bpermute_b32 v59, v67, v125
	s_waitcnt lgkmcnt(4)
	v_max_f32_e32 v58, v58, v58
	v_max_f32_e32 v85, v57, v58
	ds_bpermute_b32 v86, v81, v85
	s_waitcnt lgkmcnt(4)
	v_lshl_or_b32 v48, v48, 10, v111
	s_waitcnt lgkmcnt(3)
	v_lshl_or_b32 v49, v49, 10, v111
	s_waitcnt lgkmcnt(2)
	v_lshl_or_b32 v56, v56, 10, v111
	s_waitcnt lgkmcnt(1)
	v_lshl_or_b32 v60, v59, 10, v111
	s_waitcnt lgkmcnt(0)
; #define LAS __attribute__((address_space(3)))
; DI bf16x8 pack8(const f32x4& a, const f32x4& b) { v4u w; w.x = pk2(a[0], a[1]); w.y = pk2(a[2], a[3]); w.z = pk2(b[0], b[1]); w.w = pk2(b[2], b[3]); return __builtin_bit_cast(bf16x8, w); }
; DI void attn_unit_f8(LAS unsigned char* vbuf  , const LAS float* lut2  , const long (&qf)[4], const int* idx, int cnt_, int qpos_, int kvh, const unsigned char* K8, const bf16* VB, bf16* orow, int lane_) {
;     ...
;         float sum = 0.f;
; #pragma unroll
;         for (int kt = 0; kt < 16; ++kt)
; #pragma unroll
;             for (int e = 0; e < 4; ++e) { const float p = __builtin_amdgcn_exp2f(lg[kt][e] - mx); lg[kt][e] = p; sum += p; }
;         sum += __shfl_xor(sum, 16); sum += __shfl_xor(sum, 32);
;         inv = 1.f / sum;
; #pragma unroll
;         for (int ks = 0; ks < 8; ++ks) pf[ks] = pack8(lg[2 * ks], lg[2 * ks + 1]);
;     }
; #pragma unroll
;     for (int dt = 0; dt < 8; ++dt) o[dt] = (f32x4){0.f, 0.f, 0.f, 0.f};
; #pragma unroll
;     for (int hc = 0; hc < 16; ++hc) {
;         asm volatile("" ::: "memory");
;         const int ks = hc >> 1, par = hc & 1;
;         {
;             unsigned w0 = wx0, w1 = wx1, w2 = wx2, w3 = wx3; asm volatile("" : "+v"(w0), "+v"(w1), "+v"(w2), "+v"(w3));
; #pragma unroll
;             for (int q2 = 0; q2 < 4; ++q2) { const int xr = (par + 2 * q2) & 3; const unsigned bs = xr == 0 ? w0 : (xr == 1 ? w1 : (xr == 2 ? w2 : w3));
;                 *(LAS v4u*)(vbuf + bs + (unsigned)((ks & 1) * 8192 + 2048 * q2 + 256 * par)) = ring[(4 * hc + q2) & 15]; }
	v_max_f32_e32 v86, v86, v86
	v_max_f32_e32 v85, v85, v86
	v_sub_f32_e32 v86, v128, v85
	v_exp_f32_e32 v86, v86
	v_sub_f32_e32 v87, v129, v85
	v_exp_f32_e32 v141, v87
	v_sub_f32_e32 v87, v130, v85
	v_exp_f32_e32 v193, v87
	v_sub_f32_e32 v87, v131, v85
	v_exp_f32_e32 v194, v87
	v_sub_f32_e32 v88, v134, v85
	v_add_f32_e32 v87, 0, v86
	v_exp_f32_e32 v195, v88
	v_sub_f32_e32 v88, v135, v85
	v_add_f32_e32 v87, v141, v87
	v_exp_f32_e32 v196, v88
	v_sub_f32_e32 v88, v136, v85
	v_add_f32_e32 v87, v193, v87
	v_exp_f32_e32 v197, v88
	v_sub_f32_e32 v88, v137, v85
	v_add_f32_e32 v87, v194, v87
	v_exp_f32_e32 v198, v88
	v_sub_f32_e32 v88, v143, v85
	v_add_f32_e32 v87, v195, v87
	v_exp_f32_e32 v143, v88
	v_sub_f32_e32 v88, v144, v85
	v_add_f32_e32 v87, v196, v87
	v_exp_f32_e32 v144, v88
	v_sub_f32_e32 v88, v145, v85
	v_add_f32_e32 v87, v197, v87
	v_exp_f32_e32 v145, v88
	v_sub_f32_e32 v88, v146, v85
	v_add_f32_e32 v87, v198, v87
	v_exp_f32_e32 v146, v88
	v_sub_f32_e32 v88, v150, v85
	v_add_f32_e32 v87, v143, v87
	v_exp_f32_e32 v199, v88
	v_sub_f32_e32 v88, v151, v85
	v_add_f32_e32 v87, v144, v87
	v_exp_f32_e32 v200, v88
	v_sub_f32_e32 v88, v152, v85
	v_add_f32_e32 v87, v145, v87
	v_exp_f32_e32 v201, v88
	v_sub_f32_e32 v88, v153, v85
	v_add_f32_e32 v87, v146, v87
	v_exp_f32_e32 v202, v88
	v_sub_f32_e32 v88, v155, v85
	v_add_f32_e32 v87, v199, v87
	v_exp_f32_e32 v155, v88
	v_sub_f32_e32 v88, v156, v85
	v_add_f32_e32 v87, v200, v87
	v_exp_f32_e32 v156, v88
	v_sub_f32_e32 v88, v157, v85
	v_add_f32_e32 v87, v201, v87
	v_exp_f32_e32 v157, v88
	v_sub_f32_e32 v88, v158, v85
	v_add_f32_e32 v87, v202, v87
	v_exp_f32_e32 v158, v88
	v_sub_f32_e32 v88, v161, v85
	global_load_dwordx4 v[52:55], v48, s[46:47]
	s_nop 0
	global_load_dwordx4 v[48:51], v49, s[46:47]
	s_nop 0
	global_load_dwordx4 v[56:59], v56, s[46:47]
	s_nop 0
	global_load_dwordx4 v[60:63], v60, s[46:47]
	v_add_f32_e32 v87, v155, v87
	v_exp_f32_e32 v161, v88
	v_sub_f32_e32 v88, v162, v85
	v_add_f32_e32 v87, v156, v87
	v_exp_f32_e32 v162, v88
	v_sub_f32_e32 v88, v163, v85
	v_add_f32_e32 v87, v157, v87
	v_exp_f32_e32 v163, v88
	v_sub_f32_e32 v88, v164, v85
	v_add_f32_e32 v87, v158, v87
	v_exp_f32_e32 v164, v88
	v_sub_f32_e32 v88, v167, v85
	v_add_f32_e32 v87, v161, v87
	v_exp_f32_e32 v133, v88
	v_sub_f32_e32 v88, v168, v85
	v_add_f32_e32 v87, v162, v87
	v_exp_f32_e32 v135, v88
	v_sub_f32_e32 v88, v169, v85
	v_add_f32_e32 v87, v163, v87
	v_exp_f32_e32 v137, v88
	v_sub_f32_e32 v88, v170, v85
	v_add_f32_e32 v87, v164, v87
	v_exp_f32_e32 v139, v88
	v_sub_f32_e32 v88, v172, v85
	v_add_f32_e32 v87, v133, v87
	v_exp_f32_e32 v134, v88
	v_sub_f32_e32 v88, v173, v85
	v_add_f32_e32 v87, v135, v87
	v_exp_f32_e32 v136, v88
	v_sub_f32_e32 v88, v174, v85
	v_add_f32_e32 v87, v137, v87
	v_exp_f32_e32 v138, v88
	v_sub_f32_e32 v88, v175, v85
	v_add_f32_e32 v87, v139, v87
	v_exp_f32_e32 v140, v88
	v_sub_f32_e32 v88, v178, v85
	v_add_f32_e32 v87, v134, v87
	v_exp_f32_e32 v91, v88
	v_sub_f32_e32 v88, v179, v85
	v_lshl_add_u32 v68, v126, 4, v127
	v_add_f32_e32 v87, v136, v87
	v_exp_f32_e32 v126, v88
	v_sub_f32_e32 v88, v181, v85
	v_add_f32_e32 v87, v138, v87
	v_exp_f32_e32 v128, v88
	v_sub_f32_e32 v88, v182, v85
	v_add_f32_e32 v87, v140, v87
	v_exp_f32_e32 v130, v88
	v_sub_f32_e32 v88, v184, v85
	v_add_f32_e32 v87, v91, v87
	v_exp_f32_e32 v125, v88
	v_sub_f32_e32 v88, v185, v85
	v_add_f32_e32 v87, v126, v87
	v_exp_f32_e32 v127, v88
	v_sub_f32_e32 v88, v186, v85
	v_add_f32_e32 v87, v128, v87
	v_exp_f32_e32 v129, v88
	v_sub_f32_e32 v88, v187, v85
	v_add_f32_e32 v87, v130, v87
	v_exp_f32_e32 v131, v88
	v_add_f32_e32 v87, v125, v87
	v_add_f32_e32 v87, v127, v87
	v_add_f32_e32 v87, v129, v87
	v_add_f32_e32 v150, v131, v87
	v_sub_f32_e32 v87, v188, v85
	v_exp_f32_e32 v87, v87
	v_sub_f32_e32 v88, v189, v85
	v_exp_f32_e32 v88, v88
	v_sub_f32_e32 v89, v190, v85
	v_exp_f32_e32 v89, v89
	v_sub_f32_e32 v90, v191, v85
	v_exp_f32_e32 v90, v90
	v_add_f32_e32 v150, v87, v150
	v_add_f32_e32 v150, v88, v150
	v_add_f32_e32 v150, v89, v150
	v_or_b32_e32 v107, v123, v124
	v_bitop3_b32 v108, v123, 32, v124 bitop3:0x36
	v_bitop3_b32 v109, v123, 16, v124 bitop3:0x36
	v_add_f32_e32 v167, v90, v150
	v_cvt_pk_bf16_f32 v150, v86, v141
	v_bitop3_b32 v86, v123, 48, v124 bitop3:0x36
	v_mov_b32_e32 v123, v107
	v_mov_b32_e32 v124, v108
	v_mov_b32_e32 v141, v109
	v_mov_b32_e32 v169, v86
	v_sub_f32_e32 v168, v192, v85
	v_add_u32_e32 v123, s30, v123
	s_waitcnt vmcnt(15)
	ds_write_b128 v123, v[12:15]
	v_add_u32_e32 v12, s30, v124
	ds_bpermute_b32 v13, v64, v122
	s_waitcnt vmcnt(14)
	ds_write_b128 v12, v[4:7] offset:2048
	s_waitcnt vmcnt(13)
	ds_write_b128 v123, v[8:11] offset:4096
	ds_bpermute_b32 v4, v65, v122
	s_waitcnt vmcnt(12)
	ds_write_b128 v12, v[0:3] offset:6144
	ds_bpermute_b32 v1, v66, v122
	ds_bpermute_b32 v2, v67, v122
	s_waitcnt lgkmcnt(6)
	v_lshl_or_b32 v0, v13, 10, v111
	s_waitcnt lgkmcnt(3)
	v_lshl_or_b32 v3, v4, 10, v111
	global_load_dwordx4 v[4:7], v0, s[46:47]
	global_load_dwordx4 v[8:11], v3, s[46:47]
	s_waitcnt lgkmcnt(1)
	v_lshl_or_b32 v0, v1, 10, v111
	s_waitcnt lgkmcnt(0)
	v_lshl_or_b32 v1, v2, 10, v111
	global_load_dwordx4 v[12:15], v0, s[46:47]
	global_load_dwordx4 v[172:175], v1, s[46:47]
	v_mov_b32_e32 v0, v107
	v_mov_b32_e32 v1, v108
	v_mov_b32_e32 v2, v109
	v_mov_b32_e32 v3, v86
	v_mov_b32_e32 v122, v106
	v_add_u32_e32 v0, s30, v2
	v_add_u32_e32 v1, s30, v3
	s_waitcnt vmcnt(15)
	ds_write_b128 v0, v[20:23] offset:256
	s_waitcnt vmcnt(14)
	ds_write_b128 v1, v[16:19] offset:2304
	s_waitcnt vmcnt(13)
	ds_write_b128 v0, v[24:27] offset:4352
	s_waitcnt vmcnt(12)
	ds_write_b128 v1, v[28:31] offset:6400
	s_waitcnt lgkmcnt(0)
; #define LAS __attribute__((address_space(3)))
; #define LDS_WAIT() asm volatile("s_waitcnt lgkmcnt(0)" ::: "memory")
; #define A8_ISSUE_V(hc) do { _Pragma("unroll") for (int q2_ = 0; q2_ < 4; ++q2_) { const int rid_ = __shfl(R[hc], 4 * q2_ + g); \
;         ring[(4 * (hc) + q2_) & 15] = *(const v4u*)((const char*)VB + (unsigned)(rid_ * 1024 + kvh * 256 + 16 * lr)); } } while (0)
; #define A8_TRP(OFF) asm volatile("ds_read_b64_tr_b16 %0, %4 offset:" #OFF "\n\tds_read_b64_tr_b16 %1, %5 offset:" #OFF "\n\tds_read_b64_tr_b16 %2, %6 offset:" #OFF "\n\tds_read_b64_tr_b16 %3, %7 offset:" #OFF "\n\ts_waitcnt lgkmcnt(0)" \
;                 : "=&v"(r0), "=&v"(r1), "=&v"(r2), "=&v"(r3) : "v"(tE), "v"(tEb), "v"(tO), "v"(tOb) : "memory")
; DI void attn_unit_f8(LAS unsigned char* vbuf  , const LAS float* lut2  , const long (&qf)[4], const int* idx, int cnt_, int qpos_, int kvh, const unsigned char* K8, const bf16* VB, bf16* orow, int lane_) {
;     ...
;     for (int hc = 0; hc < 16; ++hc) {
;         asm volatile("" ::: "memory");
;         const int ks = hc >> 1, par = hc & 1;
;         {
;             unsigned w0 = wx0, w1 = wx1, w2 = wx2, w3 = wx3; asm volatile("" : "+v"(w0), "+v"(w1), "+v"(w2), "+v"(w3));
; #pragma unroll
;             for (int q2 = 0; q2 < 4; ++q2) { const int xr = (par + 2 * q2) & 3; const unsigned bs = xr == 0 ? w0 : (xr == 1 ? w1 : (xr == 2 ? w2 : w3));
;                 *(LAS v4u*)(vbuf + bs + (unsigned)((ks & 1) * 8192 + 2048 * q2 + 256 * par)) = ring[(4 * hc + q2) & 15]; }
;         }
;         if (par == 1) {
;             LDS_WAIT(); asm volatile("" ::: "memory");
;             s16x4 r0, r1, r2, r3; bf16x8 va, vb2;
;     ...
;             unsigned tE = te, tEb = teb, tO = to, tOb = tob; asm volatile("" : "+v"(tE), "+v"(tEb), "+v"(tO), "+v"(tOb));
;     ...
;             if ((ks & 1) == 0) { A8_TRP(0); A8_PV(0); A8_TRP(512); A8_PV(2); A8_TRP(1024); A8_PV(4); A8_TRP(1536); A8_PV(6); }
;             else { A8_TRP(8192); A8_PV(0); A8_TRP(8704); A8_PV(2); A8_TRP(9216); A8_PV(4); A8_TRP(9728); A8_PV(6); }
;     ...
;         }
;         if (hc + 4 < 16) A8_ISSUE_V(hc + 4);
	v_mov_b32_e32 v123, v104
	v_mov_b32_e32 v124, v105
	v_mov_b32_e32 v141, v68
	v_cvt_pk_bf16_f32 v151, v193, v194
	v_cvt_pk_bf16_f32 v152, v195, v196
	v_cvt_pk_bf16_f32 v153, v197, v198
	v_cvt_pk_bf16_f32 v188, v199, v200
	ds_read_b64_tr_b16 v[0:1], v123 offset:0
	ds_read_b64_tr_b16 v[2:3], v141 offset:0
	ds_read_b64_tr_b16 v[16:17], v124 offset:0
	ds_read_b64_tr_b16 v[18:19], v122 offset:0
	s_waitcnt lgkmcnt(0)
	ds_read_b64_tr_b16 v[28:29], v123 offset:512
	ds_read_b64_tr_b16 v[30:31], v141 offset:512
	ds_read_b64_tr_b16 v[24:25], v124 offset:512
	ds_read_b64_tr_b16 v[26:27], v122 offset:512
	s_waitcnt lgkmcnt(0)
	v_cvt_pk_bf16_f32 v189, v201, v202
	v_mfma_f32_16x16x32_bf16 v[20:23], v[0:3], v[150:153], 0
	v_exp_f32_e32 v0, v168
	v_sub_f32_e32 v1, v183, v85
	v_exp_f32_e32 v1, v1
	v_mfma_f32_16x16x32_bf16 v[16:19], v[16:19], v[150:153], 0
	v_add_f32_e32 v2, v0, v167
	v_cvt_pk_bf16_f32 v186, v143, v144
	v_add_f32_e32 v3, v1, v2
	v_sub_f32_e32 v2, v180, v85
	ds_read_b64_tr_b16 v[182:183], v123 offset:1024
	ds_read_b64_tr_b16 v[184:185], v141 offset:1024
	ds_read_b64_tr_b16 v[178:179], v124 offset:1024
	ds_read_b64_tr_b16 v[180:181], v122 offset:1024
	s_waitcnt lgkmcnt(0)
	ds_read_b64_tr_b16 v[194:195], v123 offset:1536
	ds_read_b64_tr_b16 v[196:197], v141 offset:1536
	ds_read_b64_tr_b16 v[190:191], v124 offset:1536
	ds_read_b64_tr_b16 v[192:193], v122 offset:1536
	s_waitcnt lgkmcnt(0)
	ds_bpermute_b32 v122, v64, v121
	ds_bpermute_b32 v123, v65, v121
	ds_bpermute_b32 v124, v66, v121
	ds_bpermute_b32 v121, v67, v121
	v_mfma_f32_16x16x32_bf16 v[28:31], v[28:31], v[150:153], 0
	s_waitcnt lgkmcnt(3)
	v_lshl_or_b32 v122, v122, 10, v111
	s_waitcnt lgkmcnt(2)
	v_lshl_or_b32 v123, v123, 10, v111
	v_mov_b32_e32 v141, v68
	v_mfma_f32_16x16x32_bf16 v[24:27], v[24:27], v[150:153], 0
	s_waitcnt lgkmcnt(0)
	v_lshl_or_b32 v121, v121, 10, v111
	v_cvt_pk_bf16_f32 v187, v145, v146
	ds_bpermute_b32 v146, v66, v118
	v_mfma_f32_16x16x32_bf16 v[182:185], v[182:185], v[150:153], 0
	v_exp_f32_e32 v2, v2
	v_sub_f32_e32 v145, v176, v85
	v_exp_f32_e32 v145, v145
	v_mfma_f32_16x16x32_bf16 v[178:181], v[178:181], v[150:153], 0
	v_add_f32_e32 v3, v2, v3
	v_cvt_pk_bf16_f32 v88, v87, v88
	ds_bpermute_b32 v87, v64, v113
	v_mfma_f32_16x16x32_bf16 v[194:197], v[194:197], v[150:153], 0
	v_cvt_pk_bf16_f32 v89, v89, v90
	v_cvt_pk_bf16_f32 v90, v0, v1
	ds_bpermute_b32 v0, v65, v113
	v_mfma_f32_16x16x32_bf16 v[150:153], v[190:193], v[150:153], 0
	global_load_dwordx4 v[190:193], v122, s[46:47]
	global_load_dwordx4 v[198:201], v123, s[46:47]
	v_lshl_or_b32 v122, v124, 10, v111
	global_load_dwordx4 v[202:205], v122, s[46:47]
	global_load_dwordx4 v[206:209], v121, s[46:47]
	v_mov_b32_e32 v121, v107
	v_mov_b32_e32 v122, v108
	v_mov_b32_e32 v123, v109
	v_mov_b32_e32 v124, v86
	s_waitcnt lgkmcnt(1)
	v_lshl_or_b32 v1, v87, 10, v111
	v_add_u32_e32 v121, s30, v121
	s_waitcnt vmcnt(15)
	ds_write_b128 v121, v[44:47] offset:8192
	v_add_u32_e32 v44, s30, v122
	ds_bpermute_b32 v45, v64, v120
	s_waitcnt vmcnt(14)
	ds_write_b128 v44, v[36:39] offset:10240
	s_waitcnt vmcnt(13)
	ds_write_b128 v121, v[40:43] offset:12288
	ds_bpermute_b32 v36, v65, v120
	ds_bpermute_b32 v40, v66, v120
	ds_bpermute_b32 v41, v67, v120
	s_waitcnt vmcnt(12)
	ds_write_b128 v44, v[32:35] offset:14336
	s_waitcnt lgkmcnt(6)
	v_lshl_or_b32 v32, v45, 10, v111
	s_waitcnt lgkmcnt(3)
	v_lshl_or_b32 v36, v36, 10, v111
	s_waitcnt lgkmcnt(2)
	v_lshl_or_b32 v40, v40, 10, v111
	s_waitcnt lgkmcnt(1)
	v_lshl_or_b32 v44, v41, 10, v111
	v_mov_b32_e32 v120, v107
	v_mov_b32_e32 v121, v108
	v_mov_b32_e32 v122, v109
	v_mov_b32_e32 v123, v86
	global_load_dwordx4 v[32:35], v32, s[46:47]
	s_nop 0
	global_load_dwordx4 v[36:39], v36, s[46:47]
	s_nop 0
	global_load_dwordx4 v[40:43], v40, s[46:47]
	s_nop 0
	global_load_dwordx4 v[44:47], v44, s[46:47]
	v_mov_b32_e32 v124, v105
	v_add_u32_e32 v120, s30, v122
	s_waitcnt vmcnt(15)
	ds_write_b128 v120, v[52:55] offset:8448
	v_add_u32_e32 v52, s30, v123
	s_waitcnt vmcnt(14)
	ds_write_b128 v52, v[48:51] offset:10496
	s_waitcnt vmcnt(13)
	ds_write_b128 v120, v[56:59] offset:12544
	s_waitcnt vmcnt(12)
	ds_write_b128 v52, v[60:63] offset:14592
	s_waitcnt lgkmcnt(0)
	v_mov_b32_e32 v58, v106
	v_mov_b32_e32 v59, v104
	v_cvt_pk_bf16_f32 v56, v155, v156
	ds_read_b64_tr_b16 v[52:53], v59 offset:8192
	ds_read_b64_tr_b16 v[54:55], v141 offset:8192
	ds_read_b64_tr_b16 v[48:49], v124 offset:8192
	ds_read_b64_tr_b16 v[50:51], v58 offset:8192
	s_waitcnt lgkmcnt(0)
	v_mov_b32_e32 v155, v68
	v_mfma_f32_16x16x32_bf16 v[20:23], v[52:55], v[186:189], v[20:23]
	v_sub_f32_e32 v52, v171, v85
	v_exp_f32_e32 v143, v52
	v_cvt_pk_bf16_f32 v57, v157, v158
	v_mfma_f32_16x16x32_bf16 v[16:19], v[48:51], v[186:189], v[16:19]
	ds_read_b64_tr_b16 v[52:53], v59 offset:8704
	ds_read_b64_tr_b16 v[54:55], v141 offset:8704
	ds_read_b64_tr_b16 v[48:49], v124 offset:8704
	ds_read_b64_tr_b16 v[50:51], v58 offset:8704
	s_waitcnt lgkmcnt(0)
	v_add_f32_e32 v144, v143, v3
	v_sub_f32_e32 v3, v177, v85
	v_mfma_f32_16x16x32_bf16 v[28:31], v[52:55], v[186:189], v[28:31]
	v_sub_f32_e32 v156, v165, v85
	v_exp_f32_e32 v3, v3
	ds_bpermute_b32 v87, v67, v113
	v_mfma_f32_16x16x32_bf16 v[24:27], v[48:51], v[186:189], v[24:27]
	ds_read_b64_tr_b16 v[52:53], v59 offset:9216
	ds_read_b64_tr_b16 v[54:55], v141 offset:9216
	ds_read_b64_tr_b16 v[48:49], v124 offset:9216
	ds_read_b64_tr_b16 v[50:51], v58 offset:9216
	s_waitcnt lgkmcnt(0)
	ds_read_b64_tr_b16 v[120:121], v59 offset:9728
	ds_read_b64_tr_b16 v[122:123], v141 offset:9728
	ds_read_b64_tr_b16 v[60:61], v124 offset:9728
	ds_read_b64_tr_b16 v[62:63], v58 offset:9728
	s_waitcnt lgkmcnt(0)
; #define LAS __attribute__((address_space(3)))
; #define LDS_WAIT() asm volatile("s_waitcnt lgkmcnt(0)" ::: "memory")
; #define A8_ISSUE_V(hc) do { _Pragma("unroll") for (int q2_ = 0; q2_ < 4; ++q2_) { const int rid_ = __shfl(R[hc], 4 * q2_ + g); \
;         ring[(4 * (hc) + q2_) & 15] = *(const v4u*)((const char*)VB + (unsigned)(rid_ * 1024 + kvh * 256 + 16 * lr)); } } while (0)
; #define A8_TRP(OFF) asm volatile("ds_read_b64_tr_b16 %0, %4 offset:" #OFF "\n\tds_read_b64_tr_b16 %1, %5 offset:" #OFF "\n\tds_read_b64_tr_b16 %2, %6 offset:" #OFF "\n\tds_read_b64_tr_b16 %3, %7 offset:" #OFF "\n\ts_waitcnt lgkmcnt(0)" \
;                 : "=&v"(r0), "=&v"(r1), "=&v"(r2), "=&v"(r3) : "v"(tE), "v"(tEb), "v"(tO), "v"(tOb) : "memory")
; DI void attn_unit_f8(LAS unsigned char* vbuf  , const LAS float* lut2  , const long (&qf)[4], const int* idx, int cnt_, int qpos_, int kvh, const unsigned char* K8, const bf16* VB, bf16* orow, int lane_) {
;     ...
;     for (int hc = 0; hc < 16; ++hc) {
;         asm volatile("" ::: "memory");
;         const int ks = hc >> 1, par = hc & 1;
;         {
;             unsigned w0 = wx0, w1 = wx1, w2 = wx2, w3 = wx3; asm volatile("" : "+v"(w0), "+v"(w1), "+v"(w2), "+v"(w3));
; #pragma unroll
;             for (int q2 = 0; q2 < 4; ++q2) { const int xr = (par + 2 * q2) & 3; const unsigned bs = xr == 0 ? w0 : (xr == 1 ? w1 : (xr == 2 ? w2 : w3));
;                 *(LAS v4u*)(vbuf + bs + (unsigned)((ks & 1) * 8192 + 2048 * q2 + 256 * par)) = ring[(4 * hc + q2) & 15]; }
;         }
;         if (par == 1) {
;             LDS_WAIT(); asm volatile("" ::: "memory");
;             s16x4 r0, r1, r2, r3; bf16x8 va, vb2;
;     ...
;             unsigned tE = te, tEb = teb, tO = to, tOb = tob; asm volatile("" : "+v"(tE), "+v"(tEb), "+v"(tO), "+v"(tOb));
;     ...
;             if ((ks & 1) == 0) { A8_TRP(0); A8_PV(0); A8_TRP(512); A8_PV(2); A8_TRP(1024); A8_PV(4); A8_TRP(1536); A8_PV(6); }
;             else { A8_TRP(8192); A8_PV(0); A8_TRP(8704); A8_PV(2); A8_TRP(9216); A8_PV(4); A8_TRP(9728); A8_PV(6); }
;     ...
;         }
;         if (hc + 4 < 16) A8_ISSUE_V(hc + 4);
	ds_bpermute_b32 v124, v64, v118
	ds_bpermute_b32 v141, v65, v118
	ds_bpermute_b32 v118, v67, v118
	v_mfma_f32_16x16x32_bf16 v[60:63], v[60:63], v[186:189], v[150:153]
	v_cvt_pk_bf16_f32 v58, v161, v162
	s_waitcnt lgkmcnt(2)
	v_lshl_or_b32 v124, v124, 10, v111
	s_waitcnt lgkmcnt(1)
	v_lshl_or_b32 v141, v141, 10, v111
	global_load_dwordx4 v[150:153], v124, s[46:47]
	global_load_dwordx4 v[168:171], v141, s[46:47]
	v_lshl_or_b32 v124, v146, 10, v111
	v_mfma_f32_16x16x32_bf16 v[52:55], v[52:55], v[186:189], v[182:185]
	s_waitcnt lgkmcnt(0)
	v_lshl_or_b32 v118, v118, 10, v111
	v_mov_b32_e32 v141, v109
	v_mov_b32_e32 v146, v86
	v_mfma_f32_16x16x32_bf16 v[48:51], v[48:51], v[186:189], v[178:181]
	s_nop 2
	global_load_dwordx4 v[176:179], v124, s[46:47]
	global_load_dwordx4 v[180:183], v118, s[46:47]
	v_mov_b32_e32 v118, v107
	v_mov_b32_e32 v124, v108
	v_mfma_f32_16x16x32_bf16 v[120:123], v[120:123], v[186:189], v[194:197]
	v_add_u32_e32 v118, s30, v118
	s_waitcnt vmcnt(15)
	ds_write_b128 v118, v[4:7]
	v_add_u32_e32 v4, s30, v124
	ds_bpermute_b32 v5, v64, v119
	s_waitcnt vmcnt(14)
	ds_write_b128 v4, v[8:11] offset:2048
	s_waitcnt vmcnt(13)
	ds_write_b128 v118, v[12:15] offset:4096
	ds_bpermute_b32 v6, v65, v119
	ds_bpermute_b32 v12, v66, v119
	ds_bpermute_b32 v13, v67, v119
	s_waitcnt vmcnt(12)
	ds_write_b128 v4, v[172:175] offset:6144
	s_waitcnt lgkmcnt(6)
	v_lshl_or_b32 v4, v5, 10, v111
	s_waitcnt lgkmcnt(3)
	v_lshl_or_b32 v8, v6, 10, v111
	s_waitcnt lgkmcnt(2)
	v_lshl_or_b32 v12, v12, 10, v111
	s_waitcnt lgkmcnt(1)
	v_lshl_or_b32 v118, v13, 10, v111
	global_load_dwordx4 v[4:7], v4, s[46:47]
	s_nop 0
	global_load_dwordx4 v[8:11], v8, s[46:47]
	s_nop 0
	global_load_dwordx4 v[12:15], v12, s[46:47]
	s_nop 0
	global_load_dwordx4 v[172:175], v118, s[46:47]
	v_mov_b32_e32 v118, v107
	v_mov_b32_e32 v119, v108
	v_mov_b32_e32 v124, v109
	v_mov_b32_e32 v141, v86
	v_mov_b32_e32 v146, v105
	v_add_u32_e32 v118, s30, v124
	v_add_u32_e32 v119, s30, v141
	s_waitcnt vmcnt(15)
	ds_write_b128 v118, v[190:193] offset:256
	s_waitcnt vmcnt(14)
	ds_write_b128 v119, v[198:201] offset:2304
	s_waitcnt vmcnt(13)
	ds_write_b128 v118, v[202:205] offset:4352
	s_waitcnt vmcnt(12)
	ds_write_b128 v119, v[206:209] offset:6400
	s_waitcnt lgkmcnt(0)
	v_mov_b32_e32 v124, v106
	v_mov_b32_e32 v141, v104
	v_cvt_pk_bf16_f32 v59, v163, v164
	v_sub_f32_e32 v118, v166, v85
	ds_read_b64_tr_b16 v[188:189], v141 offset:0
	ds_read_b64_tr_b16 v[190:191], v155 offset:0
	ds_read_b64_tr_b16 v[184:185], v146 offset:0
	ds_read_b64_tr_b16 v[186:187], v124 offset:0
	s_waitcnt lgkmcnt(0)
	v_exp_f32_e32 v161, v118
	v_mfma_f32_16x16x32_bf16 v[20:23], v[188:191], v[56:59], v[20:23]
	v_add_f32_e32 v118, v3, v144
	v_add_f32_e32 v118, v145, v118
	v_add_f32_e32 v144, v161, v118
	v_mfma_f32_16x16x32_bf16 v[16:19], v[184:187], v[56:59], v[16:19]
	ds_read_b64_tr_b16 v[188:189], v141 offset:512
	ds_read_b64_tr_b16 v[190:191], v155 offset:512
	ds_read_b64_tr_b16 v[184:185], v146 offset:512
	ds_read_b64_tr_b16 v[186:187], v124 offset:512
	s_waitcnt lgkmcnt(0)
	v_cvt_pk_bf16_f32 v118, v133, v135
	v_cvt_pk_bf16_f32 v119, v137, v139
	v_mfma_f32_16x16x32_bf16 v[28:31], v[188:191], v[56:59], v[28:31]
	v_mov_b32_e32 v133, v68
	v_lshl_or_b32 v0, v0, 10, v111
	v_cmp_gt_u32_e32 vcc, 4, v83
	v_mfma_f32_16x16x32_bf16 v[24:27], v[184:187], v[56:59], v[24:27]
	ds_read_b64_tr_b16 v[188:189], v141 offset:1024
	ds_read_b64_tr_b16 v[190:191], v155 offset:1024
	ds_read_b64_tr_b16 v[184:185], v146 offset:1024
	ds_read_b64_tr_b16 v[186:187], v124 offset:1024
	s_waitcnt lgkmcnt(0)
	s_nop 0
	v_mfma_f32_16x16x32_bf16 v[48:51], v[184:187], v[56:59], v[48:51]
	ds_read_b64_tr_b16 v[184:185], v141 offset:1536
	ds_read_b64_tr_b16 v[186:187], v155 offset:1536
	ds_read_b64_tr_b16 v[162:163], v146 offset:1536
	ds_read_b64_tr_b16 v[164:165], v124 offset:1536
	s_waitcnt lgkmcnt(0)
	v_mov_b32_e32 v124, v86
	v_exp_f32_e32 v146, v156
	v_mfma_f32_16x16x32_bf16 v[184:187], v[184:187], v[56:59], v[120:123]
	s_nop 2
	ds_bpermute_b32 v122, v64, v117
	v_mfma_f32_16x16x32_bf16 v[52:55], v[188:191], v[56:59], v[52:55]
	ds_bpermute_b32 v123, v65, v117
	v_cvt_pk_bf16_f32 v120, v134, v136
	v_cvt_pk_bf16_f32 v121, v138, v140
	v_mfma_f32_16x16x32_bf16 v[56:59], v[162:165], v[56:59], v[60:63]
	s_waitcnt lgkmcnt(0)
	v_lshl_or_b32 v123, v123, 10, v111
	s_nop 0
	v_lshl_or_b32 v60, v122, 10, v111
	ds_bpermute_b32 v122, v66, v117
	ds_bpermute_b32 v117, v67, v117
	global_load_dwordx4 v[60:63], v60, s[46:47]
	s_nop 0
	global_load_dwordx4 v[134:137], v123, s[46:47]
	v_mov_b32_e32 v123, v109
	s_waitcnt lgkmcnt(1)
	v_lshl_or_b32 v122, v122, 10, v111
	s_waitcnt lgkmcnt(0)
	v_lshl_or_b32 v117, v117, 10, v111
	global_load_dwordx4 v[138:141], v122, s[46:47]
	global_load_dwordx4 v[162:165], v117, s[46:47]
	v_mov_b32_e32 v117, v107
	v_mov_b32_e32 v122, v108
	s_nop 0
	v_add_u32_e32 v117, s30, v117
	s_waitcnt vmcnt(15)
	ds_write_b128 v117, v[32:35] offset:8192
	v_add_u32_e32 v32, s30, v122
	ds_bpermute_b32 v33, v64, v116
	s_waitcnt vmcnt(14)
	ds_write_b128 v32, v[36:39] offset:10240
	s_waitcnt vmcnt(13)
	ds_write_b128 v117, v[40:43] offset:12288
	ds_bpermute_b32 v34, v65, v116
	ds_bpermute_b32 v40, v66, v116
	ds_bpermute_b32 v41, v67, v116
	s_waitcnt vmcnt(12)
	ds_write_b128 v32, v[44:47] offset:14336
	s_waitcnt lgkmcnt(6)
	v_lshl_or_b32 v32, v33, 10, v111
	s_waitcnt lgkmcnt(3)
	v_lshl_or_b32 v36, v34, 10, v111
	s_waitcnt lgkmcnt(2)
	v_lshl_or_b32 v40, v40, 10, v111
	s_waitcnt lgkmcnt(1)
; #define LAS __attribute__((address_space(3)))
; #define LDS_WAIT() asm volatile("s_waitcnt lgkmcnt(0)" ::: "memory")
; #define A8_ISSUE_V(hc) do { _Pragma("unroll") for (int q2_ = 0; q2_ < 4; ++q2_) { const int rid_ = __shfl(R[hc], 4 * q2_ + g); \
;         ring[(4 * (hc) + q2_) & 15] = *(const v4u*)((const char*)VB + (unsigned)(rid_ * 1024 + kvh * 256 + 16 * lr)); } } while (0)
; #define A8_TRP(OFF) asm volatile("ds_read_b64_tr_b16 %0, %4 offset:" #OFF "\n\tds_read_b64_tr_b16 %1, %5 offset:" #OFF "\n\tds_read_b64_tr_b16 %2, %6 offset:" #OFF "\n\tds_read_b64_tr_b16 %3, %7 offset:" #OFF "\n\ts_waitcnt lgkmcnt(0)" \
;                 : "=&v"(r0), "=&v"(r1), "=&v"(r2), "=&v"(r3) : "v"(tE), "v"(tEb), "v"(tO), "v"(tOb) : "memory")
; DI void attn_unit_f8(LAS unsigned char* vbuf  , const LAS float* lut2  , const long (&qf)[4], const int* idx, int cnt_, int qpos_, int kvh, const unsigned char* K8, const bf16* VB, bf16* orow, int lane_) {
;     ...
;     for (int hc = 0; hc < 16; ++hc) {
;         asm volatile("" ::: "memory");
;         const int ks = hc >> 1, par = hc & 1;
;         {
;             unsigned w0 = wx0, w1 = wx1, w2 = wx2, w3 = wx3; asm volatile("" : "+v"(w0), "+v"(w1), "+v"(w2), "+v"(w3));
; #pragma unroll
;             for (int q2 = 0; q2 < 4; ++q2) { const int xr = (par + 2 * q2) & 3; const unsigned bs = xr == 0 ? w0 : (xr == 1 ? w1 : (xr == 2 ? w2 : w3));
;                 *(LAS v4u*)(vbuf + bs + (unsigned)((ks & 1) * 8192 + 2048 * q2 + 256 * par)) = ring[(4 * hc + q2) & 15]; }
;         }
;         if (par == 1) {
;             LDS_WAIT(); asm volatile("" ::: "memory");
;             s16x4 r0, r1, r2, r3; bf16x8 va, vb2;
;     ...
;             unsigned tE = te, tEb = teb, tO = to, tOb = tob; asm volatile("" : "+v"(tE), "+v"(tEb), "+v"(tO), "+v"(tOb));
;     ...
;             if ((ks & 1) == 0) { A8_TRP(0); A8_PV(0); A8_TRP(512); A8_PV(2); A8_TRP(1024); A8_PV(4); A8_TRP(1536); A8_PV(6); }
;             else { A8_TRP(8192); A8_PV(0); A8_TRP(8704); A8_PV(2); A8_TRP(9216); A8_PV(4); A8_TRP(9728); A8_PV(6); }
;     ...
;         }
;         if (hc + 4 < 16) A8_ISSUE_V(hc + 4);
	v_lshl_or_b32 v44, v41, 10, v111
	v_mov_b32_e32 v116, v107
	v_mov_b32_e32 v117, v108
	v_mov_b32_e32 v122, v109
	v_mov_b32_e32 v123, v86
	global_load_dwordx4 v[32:35], v32, s[46:47]
	s_nop 0
	global_load_dwordx4 v[36:39], v36, s[46:47]
	s_nop 0
	global_load_dwordx4 v[40:43], v40, s[46:47]
	s_nop 0
	global_load_dwordx4 v[44:47], v44, s[46:47]
	v_mov_b32_e32 v124, v105
	v_add_u32_e32 v116, s30, v122
	v_add_u32_e32 v117, s30, v123
	v_sub_f32_e32 v122, v160, v85
	s_waitcnt vmcnt(15)
	ds_write_b128 v116, v[150:153] offset:8448
	s_waitcnt vmcnt(14)
	ds_write_b128 v117, v[168:171] offset:10496
	s_waitcnt vmcnt(13)
	ds_write_b128 v116, v[176:179] offset:12544
	s_waitcnt vmcnt(12)
	ds_write_b128 v117, v[180:183] offset:14592
	v_exp_f32_e32 v160, v122
	s_waitcnt lgkmcnt(0)
	v_mov_b32_e32 v116, v106
	v_mov_b32_e32 v117, v104
	v_add_f32_e32 v122, v146, v144
	ds_read_b64_tr_b16 v[166:167], v117 offset:8192
	ds_read_b64_tr_b16 v[168:169], v133 offset:8192
	ds_read_b64_tr_b16 v[150:151], v124 offset:8192
	ds_read_b64_tr_b16 v[152:153], v116 offset:8192
	s_waitcnt lgkmcnt(0)
	v_add_f32_e32 v144, v160, v122
	v_mfma_f32_16x16x32_bf16 v[20:23], v[166:169], v[118:121], v[20:23]
	v_sub_f32_e32 v122, v159, v85
	v_exp_f32_e32 v176, v122
	v_cvt_pk_bf16_f32 v122, v91, v126
	v_mfma_f32_16x16x32_bf16 v[16:19], v[150:153], v[118:121], v[16:19]
	ds_read_b64_tr_b16 v[166:167], v117 offset:8704
	ds_read_b64_tr_b16 v[168:169], v133 offset:8704
	ds_read_b64_tr_b16 v[150:151], v124 offset:8704
	ds_read_b64_tr_b16 v[152:153], v116 offset:8704
	s_waitcnt lgkmcnt(0)
	ds_bpermute_b32 v91, v64, v115
	v_cvt_pk_bf16_f32 v123, v128, v130
	v_mfma_f32_16x16x32_bf16 v[24:27], v[150:153], v[118:121], v[24:27]
	ds_read_b64_tr_b16 v[156:157], v117 offset:9216
	ds_read_b64_tr_b16 v[158:159], v133 offset:9216
	ds_read_b64_tr_b16 v[150:151], v124 offset:9216
	ds_read_b64_tr_b16 v[152:153], v116 offset:9216
	s_waitcnt lgkmcnt(0)
	v_sub_f32_e32 v130, v149, v85
	s_waitcnt lgkmcnt(0)
	v_lshl_or_b32 v91, v91, 10, v111
	v_mfma_f32_16x16x32_bf16 v[52:55], v[156:159], v[118:121], v[52:55]
	v_exp_f32_e32 v130, v130
	v_mfma_f32_16x16x32_bf16 v[48:51], v[150:153], v[118:121], v[48:51]
	ds_read_b64_tr_b16 v[156:157], v117 offset:9728
	ds_read_b64_tr_b16 v[158:159], v133 offset:9728
	ds_read_b64_tr_b16 v[150:151], v124 offset:9728
	ds_read_b64_tr_b16 v[152:153], v116 offset:9728
	s_waitcnt lgkmcnt(0)
	ds_bpermute_b32 v116, v65, v115
	v_cvt_pk_bf16_f32 v124, v125, v127
	v_mfma_f32_16x16x32_bf16 v[28:31], v[166:169], v[118:121], v[28:31]
	v_cvt_pk_bf16_f32 v125, v129, v131
	v_mfma_f32_16x16x32_bf16 v[156:159], v[156:159], v[118:121], v[184:187]
	v_mfma_f32_16x16x32_bf16 v[56:59], v[150:153], v[118:121], v[56:59]
	ds_bpermute_b32 v120, v66, v115
	ds_bpermute_b32 v115, v67, v115
	s_waitcnt lgkmcnt(2)
	v_lshl_or_b32 v121, v116, 10, v111
	global_load_dwordx4 v[116:119], v91, s[46:47]
	global_load_dwordx4 v[126:129], v121, s[46:47]
	v_mov_b32_e32 v121, v86
	s_waitcnt lgkmcnt(1)
	v_lshl_or_b32 v91, v120, 10, v111
	s_waitcnt lgkmcnt(0)
	v_lshl_or_b32 v115, v115, 10, v111
	global_load_dwordx4 v[150:153], v91, s[46:47]
	global_load_dwordx4 v[166:169], v115, s[46:47]
	v_mov_b32_e32 v91, v107
	v_mov_b32_e32 v115, v108
	v_mov_b32_e32 v120, v109
	s_nop 0
	v_add_u32_e32 v91, s30, v91
	s_waitcnt vmcnt(15)
	ds_write_b128 v91, v[4:7]
	v_add_u32_e32 v4, s30, v115
	ds_bpermute_b32 v5, v64, v114
	s_waitcnt vmcnt(14)
	ds_write_b128 v4, v[8:11] offset:2048
	s_waitcnt vmcnt(13)
	ds_write_b128 v91, v[12:15] offset:4096
	ds_bpermute_b32 v6, v65, v114
	ds_bpermute_b32 v12, v66, v114
	ds_bpermute_b32 v13, v67, v114
	s_waitcnt vmcnt(12)
	ds_write_b128 v4, v[172:175] offset:6144
	s_waitcnt lgkmcnt(6)
	v_lshl_or_b32 v4, v5, 10, v111
	s_waitcnt lgkmcnt(3)
	v_lshl_or_b32 v8, v6, 10, v111
	s_waitcnt lgkmcnt(2)
	v_lshl_or_b32 v12, v12, 10, v111
	s_waitcnt lgkmcnt(1)
	v_lshl_or_b32 v91, v13, 10, v111
	global_load_dwordx4 v[4:7], v4, s[46:47]
	s_nop 0
	global_load_dwordx4 v[8:11], v8, s[46:47]
	s_nop 0
	global_load_dwordx4 v[12:15], v12, s[46:47]
	s_nop 0
	global_load_dwordx4 v[170:173], v91, s[46:47]
	v_mov_b32_e32 v91, v107
	v_mov_b32_e32 v114, v108
	v_mov_b32_e32 v115, v109
	v_mov_b32_e32 v120, v86
	v_add_f32_e32 v121, v176, v144
	v_add_u32_e32 v91, s30, v115
	s_waitcnt vmcnt(15)
	ds_write_b128 v91, v[60:63] offset:256
	v_add_u32_e32 v60, s30, v120
	s_waitcnt vmcnt(14)
	ds_write_b128 v60, v[134:137] offset:2304
	s_waitcnt vmcnt(13)
	ds_write_b128 v91, v[138:141] offset:4352
	s_waitcnt vmcnt(12)
	ds_write_b128 v60, v[162:165] offset:6400
	s_waitcnt lgkmcnt(0)
	v_mov_b32_e32 v91, v106
	v_mov_b32_e32 v114, v104
	v_mov_b32_e32 v115, v105
	v_mov_b32_e32 v120, v68
	v_add_f32_e32 v131, v130, v121
	ds_read_b64_tr_b16 v[134:135], v114 offset:0
	ds_read_b64_tr_b16 v[136:137], v120 offset:0
	ds_read_b64_tr_b16 v[60:61], v115 offset:0
	ds_read_b64_tr_b16 v[62:63], v91 offset:0
	s_waitcnt lgkmcnt(0)
	v_sub_f32_e32 v121, v148, v85
	v_mfma_f32_16x16x32_bf16 v[20:23], v[134:137], v[122:125], v[20:23]
	v_exp_f32_e32 v133, v121
	v_sub_f32_e32 v144, v154, v85
	v_mfma_f32_16x16x32_bf16 v[16:19], v[60:63], v[122:125], v[16:19]
	ds_read_b64_tr_b16 v[134:135], v114 offset:512
	ds_read_b64_tr_b16 v[136:137], v120 offset:512
	ds_read_b64_tr_b16 v[60:61], v115 offset:512
	ds_read_b64_tr_b16 v[62:63], v91 offset:512
	s_waitcnt lgkmcnt(0)
	s_nop 0
	v_mfma_f32_16x16x32_bf16 v[28:31], v[134:137], v[122:125], v[28:31]
	v_mfma_f32_16x16x32_bf16 v[24:27], v[60:63], v[122:125], v[24:27]
	ds_read_b64_tr_b16 v[134:135], v114 offset:1024
	ds_read_b64_tr_b16 v[136:137], v120 offset:1024
	ds_read_b64_tr_b16 v[60:61], v115 offset:1024
	ds_read_b64_tr_b16 v[62:63], v91 offset:1024
	s_waitcnt lgkmcnt(0)
; #define LAS __attribute__((address_space(3)))
; #define LDS_WAIT() asm volatile("s_waitcnt lgkmcnt(0)" ::: "memory")
; #define A8_ISSUE_V(hc) do { _Pragma("unroll") for (int q2_ = 0; q2_ < 4; ++q2_) { const int rid_ = __shfl(R[hc], 4 * q2_ + g); \
;         ring[(4 * (hc) + q2_) & 15] = *(const v4u*)((const char*)VB + (unsigned)(rid_ * 1024 + kvh * 256 + 16 * lr)); } } while (0)
; #define A8_TRP(OFF) asm volatile("ds_read_b64_tr_b16 %0, %4 offset:" #OFF "\n\tds_read_b64_tr_b16 %1, %5 offset:" #OFF "\n\tds_read_b64_tr_b16 %2, %6 offset:" #OFF "\n\tds_read_b64_tr_b16 %3, %7 offset:" #OFF "\n\ts_waitcnt lgkmcnt(0)" \
;                 : "=&v"(r0), "=&v"(r1), "=&v"(r2), "=&v"(r3) : "v"(tE), "v"(tEb), "v"(tO), "v"(tOb) : "memory")
; DI void attn_unit_f8(LAS unsigned char* vbuf  , const LAS float* lut2  , const long (&qf)[4], const int* idx, int cnt_, int qpos_, int kvh, const unsigned char* K8, const bf16* VB, bf16* orow, int lane_) {
;     ...
;     for (int hc = 0; hc < 16; ++hc) {
;         asm volatile("" ::: "memory");
;         const int ks = hc >> 1, par = hc & 1;
;         {
;             unsigned w0 = wx0, w1 = wx1, w2 = wx2, w3 = wx3; asm volatile("" : "+v"(w0), "+v"(w1), "+v"(w2), "+v"(w3));
; #pragma unroll
;             for (int q2 = 0; q2 < 4; ++q2) { const int xr = (par + 2 * q2) & 3; const unsigned bs = xr == 0 ? w0 : (xr == 1 ? w1 : (xr == 2 ? w2 : w3));
;                 *(LAS v4u*)(vbuf + bs + (unsigned)((ks & 1) * 8192 + 2048 * q2 + 256 * par)) = ring[(4 * hc + q2) & 15]; }
;         }
;         if (par == 1) {
;             LDS_WAIT(); asm volatile("" ::: "memory");
;             s16x4 r0, r1, r2, r3; bf16x8 va, vb2;
;     ...
;             unsigned tE = te, tEb = teb, tO = to, tOb = tob; asm volatile("" : "+v"(tE), "+v"(tEb), "+v"(tO), "+v"(tOb));
;     ...
;             if ((ks & 1) == 0) { A8_TRP(0); A8_PV(0); A8_TRP(512); A8_PV(2); A8_TRP(1024); A8_PV(4); A8_TRP(1536); A8_PV(6); }
;             else { A8_TRP(8192); A8_PV(0); A8_TRP(8704); A8_PV(2); A8_TRP(9216); A8_PV(4); A8_TRP(9728); A8_PV(6); }
;     ...
;         }
;         if (hc + 4 < 16) A8_ISSUE_V(hc + 4);
	s_nop 0
	v_mfma_f32_16x16x32_bf16 v[52:55], v[134:137], v[122:125], v[52:55]
	v_mfma_f32_16x16x32_bf16 v[48:51], v[60:63], v[122:125], v[48:51]
	ds_read_b64_tr_b16 v[134:135], v114 offset:1536
	ds_read_b64_tr_b16 v[136:137], v120 offset:1536
	ds_read_b64_tr_b16 v[60:61], v115 offset:1536
	ds_read_b64_tr_b16 v[62:63], v91 offset:1536
	s_waitcnt lgkmcnt(0)
	v_cvt_pk_bf16_f32 v91, v2, v143
	ds_bpermute_b32 v2, v66, v113
	v_mfma_f32_16x16x32_bf16 v[134:137], v[134:137], v[122:125], v[156:159]
	v_mfma_f32_16x16x32_bf16 v[56:59], v[60:63], v[122:125], v[56:59]
	global_load_dwordx4 v[60:63], v1, s[46:47]
	global_load_dwordx4 v[120:123], v0, s[46:47]
	s_waitcnt lgkmcnt(0)
	v_lshl_or_b32 v0, v2, 10, v111
	v_lshl_or_b32 v1, v87, 10, v111
	global_load_dwordx4 v[138:141], v0, s[46:47]
	global_load_dwordx4 v[154:157], v1, s[46:47]
	v_mov_b32_e32 v0, v107
	v_mov_b32_e32 v1, v108
	v_mov_b32_e32 v2, v109
	v_mov_b32_e32 v87, v86
	ds_bpermute_b32 v2, v64, v112
	v_add_u32_e32 v0, s30, v0
	v_add_u32_e32 v1, s30, v1
	s_waitcnt vmcnt(15)
	ds_write_b128 v0, v[32:35] offset:8192
	s_waitcnt vmcnt(14)
	ds_write_b128 v1, v[36:39] offset:10240
	s_waitcnt vmcnt(13)
	ds_write_b128 v0, v[40:43] offset:12288
	ds_bpermute_b32 v0, v65, v112
	s_waitcnt vmcnt(12)
	ds_write_b128 v1, v[44:47] offset:14336
	s_waitcnt lgkmcnt(5)
	v_lshl_or_b32 v1, v2, 10, v111
	ds_bpermute_b32 v2, v66, v112
	ds_bpermute_b32 v40, v67, v112
	s_waitcnt lgkmcnt(3)
	v_lshl_or_b32 v0, v0, 10, v111
	global_load_dwordx4 v[32:35], v1, s[46:47]
	global_load_dwordx4 v[36:39], v0, s[46:47]
	v_mov_b32_e32 v87, v86
	s_waitcnt lgkmcnt(1)
	v_lshl_or_b32 v0, v2, 10, v111
	s_waitcnt lgkmcnt(0)
	v_lshl_or_b32 v1, v40, 10, v111
	global_load_dwordx4 v[40:43], v0, s[46:47]
	global_load_dwordx4 v[44:47], v1, s[46:47]
	v_mov_b32_e32 v0, v107
	v_mov_b32_e32 v1, v108
	v_mov_b32_e32 v2, v109
	v_mov_b32_e32 v124, v105
	v_add_u32_e32 v0, s30, v2
	v_add_u32_e32 v1, s30, v87
	s_waitcnt vmcnt(15)
	ds_write_b128 v0, v[116:119] offset:8448
	s_waitcnt vmcnt(14)
	ds_write_b128 v1, v[126:129] offset:10496
	s_waitcnt vmcnt(13)
	ds_write_b128 v0, v[150:153] offset:12544
	s_waitcnt vmcnt(12)
	ds_write_b128 v1, v[166:169] offset:14592
	s_waitcnt lgkmcnt(0)
	v_mov_b32_e32 v2, v106
	v_mov_b32_e32 v87, v104
	v_mov_b32_e32 v125, v68
	ds_bpermute_b32 v64, v64, v110
	ds_read_b64_tr_b16 v[116:117], v87 offset:8192
	ds_read_b64_tr_b16 v[118:119], v125 offset:8192
	ds_read_b64_tr_b16 v[112:113], v124 offset:8192
	ds_read_b64_tr_b16 v[114:115], v2 offset:8192
	s_waitcnt lgkmcnt(0)
	ds_bpermute_b32 v65, v65, v110
	v_mfma_f32_16x16x32_bf16 v[20:23], v[116:119], v[88:91], v[20:23]
	v_sub_f32_e32 v0, v147, v85
	s_waitcnt lgkmcnt(1)
	v_lshl_or_b32 v64, v64, 10, v111
	v_exp_f32_e32 v129, v0
	v_mfma_f32_16x16x32_bf16 v[16:19], v[112:115], v[88:91], v[16:19]
	ds_read_b64_tr_b16 v[116:117], v87 offset:8704
	ds_read_b64_tr_b16 v[118:119], v125 offset:8704
	ds_read_b64_tr_b16 v[112:113], v124 offset:8704
	ds_read_b64_tr_b16 v[114:115], v2 offset:8704
	s_waitcnt lgkmcnt(0)
	v_sub_f32_e32 v0, v132, v85
	v_exp_f32_e32 v132, v0
	v_mfma_f32_16x16x32_bf16 v[28:31], v[116:119], v[88:91], v[28:31]
	v_sub_f32_e32 v0, v142, v85
	v_exp_f32_e32 v142, v0
	v_cvt_pk_bf16_f32 v0, v3, v145
	v_mfma_f32_16x16x32_bf16 v[24:27], v[112:115], v[88:91], v[24:27]
	ds_read_b64_tr_b16 v[116:117], v87 offset:9216
	ds_read_b64_tr_b16 v[118:119], v125 offset:9216
	ds_read_b64_tr_b16 v[112:113], v124 offset:9216
	ds_read_b64_tr_b16 v[114:115], v2 offset:9216
	s_waitcnt lgkmcnt(0)
	v_cvt_pk_bf16_f32 v3, v130, v133
	v_mov_b32_e32 v130, v86
	v_mfma_f32_16x16x32_bf16 v[52:55], v[116:119], v[88:91], v[52:55]
	v_cvt_pk_bf16_f32 v1, v161, v146
	v_exp_f32_e32 v128, v144
	v_mfma_f32_16x16x32_bf16 v[48:51], v[112:115], v[88:91], v[48:51]
	ds_read_b64_tr_b16 v[116:117], v87 offset:9728
	ds_read_b64_tr_b16 v[118:119], v125 offset:9728
	ds_read_b64_tr_b16 v[112:113], v124 offset:9728
	ds_read_b64_tr_b16 v[114:115], v2 offset:9728
	s_waitcnt lgkmcnt(0)
	ds_bpermute_b32 v87, v66, v110
	ds_bpermute_b32 v110, v67, v110
	v_mfma_f32_16x16x32_bf16 v[116:119], v[116:119], v[88:91], v[134:137]
	v_cvt_pk_bf16_f32 v2, v160, v176
	s_waitcnt lgkmcnt(1)
	v_lshl_or_b32 v87, v87, 10, v111
	v_mfma_f32_16x16x32_bf16 v[56:59], v[112:115], v[88:91], v[56:59]
	v_lshl_or_b32 v88, v65, 10, v111
	global_load_dwordx4 v[64:67], v64, s[46:47]
	s_nop 0
	global_load_dwordx4 v[88:91], v88, s[46:47]
	s_waitcnt lgkmcnt(0)
	v_lshl_or_b32 v114, v110, 10, v111
	global_load_dwordx4 v[110:113], v87, s[46:47]
	global_load_dwordx4 v[124:127], v114, s[46:47]
	v_mov_b32_e32 v87, v107
	v_mov_b32_e32 v114, v108
	v_mov_b32_e32 v115, v109
	s_nop 0
	v_add_u32_e32 v87, s30, v87
	s_waitcnt vmcnt(15)
	ds_write_b128 v87, v[4:7]
	v_add_u32_e32 v4, s30, v114
	s_waitcnt vmcnt(14)
	ds_write_b128 v4, v[8:11] offset:2048
	s_waitcnt vmcnt(13)
	ds_write_b128 v87, v[12:15] offset:4096
	s_waitcnt vmcnt(12)
	ds_write_b128 v4, v[170:173] offset:6144
	v_mov_b32_e32 v4, v107
	v_mov_b32_e32 v5, v108
	v_mov_b32_e32 v6, v109
	v_mov_b32_e32 v7, v86
	v_mov_b32_e32 v87, v68
	v_add_u32_e32 v4, s30, v6
	v_add_u32_e32 v5, s30, v7
	s_waitcnt vmcnt(11)
	ds_write_b128 v4, v[60:63] offset:256
	s_waitcnt vmcnt(10)
	ds_write_b128 v5, v[120:123] offset:2304
	s_waitcnt vmcnt(9)
	ds_write_b128 v4, v[138:141] offset:4352
	s_waitcnt vmcnt(8)
	ds_write_b128 v5, v[154:157] offset:6400
	s_waitcnt lgkmcnt(0)
	v_mov_b32_e32 v61, v106
	v_mov_b32_e32 v62, v104
	v_mov_b32_e32 v63, v105
	v_sub_f32_e32 v12, v71, v85
	ds_read_b64_tr_b16 v[8:9], v62 offset:0
	ds_read_b64_tr_b16 v[10:11], v87 offset:0
	ds_read_b64_tr_b16 v[4:5], v63 offset:0
	ds_read_b64_tr_b16 v[6:7], v61 offset:0
	s_waitcnt lgkmcnt(0)
; #define LAS __attribute__((address_space(3)))
; DI unsigned pk2(float lo, float hi) { const f32x2 v = {lo, hi}; return __builtin_bit_cast(unsigned, __builtin_convertvector(v, bf16x2_t)); }
; #define LDS_WAIT() asm volatile("s_waitcnt lgkmcnt(0)" ::: "memory")
; #define A8_ISSUE_V(hc) do { _Pragma("unroll") for (int q2_ = 0; q2_ < 4; ++q2_) { const int rid_ = __shfl(R[hc], 4 * q2_ + g); \
;         ring[(4 * (hc) + q2_) & 15] = *(const v4u*)((const char*)VB + (unsigned)(rid_ * 1024 + kvh * 256 + 16 * lr)); } } while (0)
; DI void attn_unit_f8(LAS unsigned char* vbuf  , const LAS float* lut2  , const long (&qf)[4], const int* idx, int cnt_, int qpos_, int kvh, const unsigned char* K8, const bf16* VB, bf16* orow, int lane_) {
;     ...
;         sum += __shfl_xor(sum, 16); sum += __shfl_xor(sum, 32);
;         inv = 1.f / sum;
;     ...
;     for (int hc = 0; hc < 16; ++hc) {
;         asm volatile("" ::: "memory");
;         const int ks = hc >> 1, par = hc & 1;
;         {
;             unsigned w0 = wx0, w1 = wx1, w2 = wx2, w3 = wx3; asm volatile("" : "+v"(w0), "+v"(w1), "+v"(w2), "+v"(w3));
; #pragma unroll
;             for (int q2 = 0; q2 < 4; ++q2) { const int xr = (par + 2 * q2) & 3; const unsigned bs = xr == 0 ? w0 : (xr == 1 ? w1 : (xr == 2 ? w2 : w3));
;                 *(LAS v4u*)(vbuf + bs + (unsigned)((ks & 1) * 8192 + 2048 * q2 + 256 * par)) = ring[(4 * hc + q2) & 15]; }
;         }
;         if (par == 1) {
;             LDS_WAIT(); asm volatile("" ::: "memory");
;             s16x4 r0, r1, r2, r3; bf16x8 va, vb2;
;     ...
;             unsigned tE = te, tEb = teb, tO = to, tOb = tob; asm volatile("" : "+v"(tE), "+v"(tEb), "+v"(tO), "+v"(tOb));
;     ...
;             if ((ks & 1) == 0) { A8_TRP(0); A8_PV(0); A8_TRP(512); A8_PV(2); A8_TRP(1024); A8_PV(4); A8_TRP(1536); A8_PV(6); }
;             else { A8_TRP(8192); A8_PV(0); A8_TRP(8704); A8_PV(2); A8_TRP(9216); A8_PV(4); A8_TRP(9728); A8_PV(6); }
;     ...
;         }
;         if (hc + 4 < 16) A8_ISSUE_V(hc + 4);
;     }
;     if (lr < 4) {
; #pragma unroll
;         for (int dt = 0; dt < 8; ++dt) { v2u w; w.x = pk2(o[dt][0] * inv, o[dt][1] * inv); w.y = pk2(o[dt][2] * inv, o[dt][3] * inv); *(v2u*)(orow + (4 * kvh + lr) * 128 + 16 * dt + 4 * g) = w; } }
	v_exp_f32_e32 v71, v12
	v_mfma_f32_16x16x32_bf16 v[8:11], v[8:11], v[0:3], v[20:23]
	v_cvt_pk_bf16_f32 v60, v128, v129
	s_nop 1
	v_sub_f32_e32 v20, v84, v85
	v_mfma_f32_16x16x32_bf16 v[4:7], v[4:7], v[0:3], v[16:19]
	ds_read_b64_tr_b16 v[16:17], v62 offset:512
	ds_read_b64_tr_b16 v[18:19], v87 offset:512
	ds_read_b64_tr_b16 v[12:13], v63 offset:512
	ds_read_b64_tr_b16 v[14:15], v61 offset:512
	s_waitcnt lgkmcnt(0)
	v_exp_f32_e32 v84, v20
	v_sub_f32_e32 v20, v70, v85
	v_exp_f32_e32 v70, v20
	v_mfma_f32_16x16x32_bf16 v[12:15], v[12:15], v[0:3], v[24:27]
	ds_read_b64_tr_b16 v[24:25], v62 offset:1024
	ds_read_b64_tr_b16 v[26:27], v87 offset:1024
	ds_read_b64_tr_b16 v[20:21], v63 offset:1024
	ds_read_b64_tr_b16 v[22:23], v61 offset:1024
	s_waitcnt lgkmcnt(0)
	s_nop 0
	v_mfma_f32_16x16x32_bf16 v[52:55], v[24:27], v[0:3], v[52:55]
	s_nop 0
	v_sub_f32_e32 v24, v69, v85
	v_exp_f32_e32 v69, v24
	v_mfma_f32_16x16x32_bf16 v[48:51], v[20:23], v[0:3], v[48:51]
	ds_read_b64_tr_b16 v[24:25], v62 offset:1536
	ds_read_b64_tr_b16 v[26:27], v87 offset:1536
	ds_read_b64_tr_b16 v[20:21], v63 offset:1536
	ds_read_b64_tr_b16 v[22:23], v61 offset:1536
	s_waitcnt lgkmcnt(0)
	v_cvt_pk_bf16_f32 v61, v132, v142
	v_mfma_f32_16x16x32_bf16 v[16:19], v[16:19], v[0:3], v[28:31]
	v_cvt_pk_bf16_f32 v62, v71, v84
	v_cvt_pk_bf16_f32 v63, v70, v69
	v_mfma_f32_16x16x32_bf16 v[114:117], v[24:27], v[0:3], v[116:119]
	v_mfma_f32_16x16x32_bf16 v[0:3], v[20:23], v[0:3], v[56:59]
	v_mov_b32_e32 v20, v107
	v_mov_b32_e32 v21, v108
	v_mov_b32_e32 v22, v109
	v_mov_b32_e32 v23, v86
	s_nop 0
	v_add_u32_e32 v20, s30, v20
	v_add_u32_e32 v21, s30, v21
	s_waitcnt vmcnt(7)
	ds_write_b128 v20, v[32:35] offset:8192
	s_waitcnt vmcnt(6)
	ds_write_b128 v21, v[36:39] offset:10240
	s_waitcnt vmcnt(5)
	ds_write_b128 v20, v[40:43] offset:12288
	s_waitcnt vmcnt(4)
	ds_write_b128 v21, v[44:47] offset:14336
	s_nop 0
	v_add_u32_e32 v20, s30, v109
	v_add_u32_e32 v21, s30, v86
	s_waitcnt vmcnt(3)
	ds_write_b128 v20, v[64:67] offset:8448
	s_waitcnt vmcnt(2)
	ds_write_b128 v21, v[88:91] offset:10496
	s_waitcnt vmcnt(1)
	ds_write_b128 v20, v[110:113] offset:12544
	s_waitcnt vmcnt(0)
	ds_write_b128 v21, v[124:127] offset:14592
	s_waitcnt lgkmcnt(0)
	s_nop 0
	ds_read_b64_tr_b16 v[24:25], v104 offset:8192
	ds_read_b64_tr_b16 v[26:27], v68 offset:8192
	ds_read_b64_tr_b16 v[20:21], v105 offset:8192
	ds_read_b64_tr_b16 v[22:23], v106 offset:8192
	s_waitcnt lgkmcnt(0)
	s_nop 0
	v_mfma_f32_16x16x32_bf16 v[28:31], v[24:27], v[60:63], v[8:11]
	s_nop 2
	v_add_f32_e32 v8, v133, v131
	v_add_f32_e32 v8, v128, v8
	v_add_f32_e32 v32, v129, v8
	v_mfma_f32_16x16x32_bf16 v[20:23], v[20:23], v[60:63], v[4:7]
	ds_read_b64_tr_b16 v[8:9], v104 offset:8704
	ds_read_b64_tr_b16 v[10:11], v68 offset:8704
	ds_read_b64_tr_b16 v[4:5], v105 offset:8704
	ds_read_b64_tr_b16 v[6:7], v106 offset:8704
	s_waitcnt lgkmcnt(0)
	s_nop 0
	v_mfma_f32_16x16x32_bf16 v[24:27], v[8:11], v[60:63], v[16:19]
	v_add_f32_e32 v8, v132, v32
	v_add_f32_e32 v8, v142, v8
	v_add_f32_e32 v32, v71, v8
	v_mfma_f32_16x16x32_bf16 v[12:15], v[4:7], v[60:63], v[12:15]
	ds_read_b64_tr_b16 v[8:9], v104 offset:9216
	ds_read_b64_tr_b16 v[10:11], v68 offset:9216
	ds_read_b64_tr_b16 v[4:5], v105 offset:9216
	ds_read_b64_tr_b16 v[6:7], v106 offset:9216
	s_waitcnt lgkmcnt(0)
	s_nop 0
	v_mfma_f32_16x16x32_bf16 v[16:19], v[8:11], v[60:63], v[52:55]
	v_add_f32_e32 v8, v84, v32
	v_add_f32_e32 v8, v70, v8
	v_add_f32_e32 v32, v69, v8
	ds_bpermute_b32 v33, v72, v32
	ds_read_b64_tr_b16 v[8:9], v104 offset:9728
	ds_read_b64_tr_b16 v[10:11], v68 offset:9728
	ds_read_b64_tr_b16 v[34:35], v105 offset:9728
	ds_read_b64_tr_b16 v[36:37], v106 offset:9728
	s_waitcnt lgkmcnt(0)
	v_mfma_f32_16x16x32_bf16 v[4:7], v[4:7], v[60:63], v[48:51]
	s_waitcnt lgkmcnt(0)
	v_add_f32_e32 v32, v32, v33
	ds_bpermute_b32 v33, v81, v32
	v_mfma_f32_16x16x32_bf16 v[8:11], v[8:11], v[60:63], v[114:117]
	v_mfma_f32_16x16x32_bf16 v[0:3], v[34:37], v[60:63], v[0:3]
	s_and_saveexec_b64 s[8:9], vcc
	s_xor_b64 s[8:9], exec, s[8:9]
	s_cbranch_execz .LBB0_5549
	s_waitcnt lgkmcnt(0)
	v_add_f32_e32 v32, v32, v33
	s_lshl_b64 s[10:11], s[52:53], 11
	s_lshl_b64 s[10:11], s[10:11], 1
	s_add_u32 s10, s57, s10
	v_rcp_f32_e32 v32, v32
	v_or_b32_e32 v33, s54, v83
	s_addc_u32 s11, s58, s11
	v_lshlrev_b32_e32 v72, 8, v33
	v_lshl_add_u64 v[34:35], s[10:11], 0, v[72:73]
	v_ashrrev_i32_e32 v83, 31, v82
	v_pk_mul_f32 v[20:21], v[32:33], v[20:21] op_sel_hi:[0,1]
	v_pk_mul_f32 v[22:23], v[32:33], v[22:23] op_sel_hi:[0,1]
	v_pk_mul_f32 v[12:13], v[32:33], v[12:13] op_sel_hi:[0,1]
	v_pk_mul_f32 v[14:15], v[32:33], v[14:15] op_sel_hi:[0,1]
	v_pk_mul_f32 v[4:5], v[32:33], v[4:5] op_sel_hi:[0,1]
	v_pk_mul_f32 v[6:7], v[32:33], v[6:7] op_sel_hi:[0,1]
	v_lshl_add_u64 v[34:35], v[82:83], 1, v[34:35]
	v_cvt_pk_bf16_f32 v20, v20, v21
	v_cvt_pk_bf16_f32 v21, v22, v23
	v_cvt_pk_bf16_f32 v12, v12, v13
	v_cvt_pk_bf16_f32 v13, v14, v15
	v_cvt_pk_bf16_f32 v4, v4, v5
	v_cvt_pk_bf16_f32 v5, v6, v7
	v_pk_mul_f32 v[28:29], v[32:33], v[28:29] op_sel_hi:[0,1]
	v_pk_mul_f32 v[30:31], v[32:33], v[30:31] op_sel_hi:[0,1]
	global_store_dwordx2 v[34:35], v[20:21], off offset:32
	v_pk_mul_f32 v[20:21], v[32:33], v[24:25] op_sel_hi:[0,1]
	v_pk_mul_f32 v[22:23], v[32:33], v[26:27] op_sel_hi:[0,1]
	global_store_dwordx2 v[34:35], v[12:13], off offset:96
	v_pk_mul_f32 v[12:13], v[32:33], v[16:17] op_sel_hi:[0,1]
	v_pk_mul_f32 v[14:15], v[32:33], v[18:19] op_sel_hi:[0,1]
	global_store_dwordx2 v[34:35], v[4:5], off offset:160
	v_pk_mul_f32 v[4:5], v[32:33], v[8:9] op_sel_hi:[0,1]
	v_pk_mul_f32 v[6:7], v[32:33], v[10:11] op_sel_hi:[0,1]
	v_pk_mul_f32 v[0:1], v[32:33], v[0:1] op_sel_hi:[0,1]
	v_pk_mul_f32 v[2:3], v[32:33], v[2:3] op_sel_hi:[0,1]
	v_cvt_pk_bf16_f32 v28, v28, v29
	v_cvt_pk_bf16_f32 v29, v30, v31
	v_cvt_pk_bf16_f32 v20, v20, v21
	v_cvt_pk_bf16_f32 v21, v22, v23
	v_cvt_pk_bf16_f32 v12, v12, v13
	v_cvt_pk_bf16_f32 v13, v14, v15
	v_cvt_pk_bf16_f32 v4, v4, v5
	v_cvt_pk_bf16_f32 v5, v6, v7
	v_cvt_pk_bf16_f32 v0, v0, v1
	v_cvt_pk_bf16_f32 v1, v2, v3
	global_store_dwordx2 v[34:35], v[28:29], off
	global_store_dwordx2 v[34:35], v[20:21], off offset:64
	global_store_dwordx2 v[34:35], v[12:13], off offset:128
	global_store_dwordx2 v[34:35], v[4:5], off offset:192
	global_store_dwordx2 v[34:35], v[0:1], off offset:224
